# adds: GLA bf16 select via one v_perm_b32 instead of shift+and; attention loops: dropped compiler pad nops between v_max3, ds_read moved into the exp->add wait slot, removed +0 adds
# speedup vs baseline: 1.0015x; 1.0015x over previous
.LBB0_844:
	v_max3_f32 v170, v231, v82, v83
	v_max3_f32 v220, v170, v84, v85
	s_waitcnt lgkmcnt(1)
	v_mfma_f32_32x32x16_bf16 v[18:33], v[174:177], v[166:169], v[18:33]
	ds_read2_b64 v[170:173], v208 offset0:36 offset1:38
	v_cndmask_b32_e64 v166, 0, 1, s[2:3]
	v_cmp_ne_u32_e64 s[0:1], 1, v166
	s_andn2_b64 vcc, exec, s[2:3]
	s_cbranch_vccnz .LBB0_846
	v_add_u32_e32 v166, 55, v240
	v_cmp_lt_u32_e32 vcc, s95, v166
	v_add_u32_e32 v166, 54, v240
	s_nop 0
	v_cndmask_b32_e32 v86, v243, v86, vcc
	v_cmp_lt_u32_e32 vcc, s95, v166
	v_add_u32_e32 v166, 53, v240
	s_nop 0
	v_cndmask_b32_e32 v87, v243, v87, vcc
	v_cmp_lt_u32_e32 vcc, s95, v166
	v_add_u32_e32 v166, 52, v240
	s_nop 0
	v_cndmask_b32_e32 v88, v243, v88, vcc
	v_cmp_lt_u32_e32 vcc, s95, v166
	s_nop 1
	v_cndmask_b32_e32 v89, v243, v89, vcc
.LBB0_846:
	v_exp_f32_e32 v204, v42
	v_exp_f32_e32 v205, v43
	v_exp_f32_e32 v214, v44
	v_exp_f32_e32 v215, v45
	v_exp_f32_e32 v216, v46
	v_exp_f32_e32 v217, v47
	v_exp_f32_e32 v218, v48
	v_exp_f32_e32 v219, v49
	v_cvt_pk_bf16_f32 v178, v204, v205
	v_cvt_pk_bf16_f32 v179, v214, v215
	v_cvt_pk_bf16_f32 v180, v216, v217
	v_cvt_pk_bf16_f32 v181, v218, v219
	v_max3_f32 v166, v220, v86, v87
	v_max3_f32 v174, v166, v88, v89
	s_waitcnt lgkmcnt(1)
	v_mfma_f32_32x32x16_bf16 v[2:17], v[162:165], v[178:181], v[2:17]
	ds_read2_b64 v[166:169], v224 offset0:8 offset1:10
	s_and_b64 vcc, exec, s[0:1]
	s_cbranch_vccnz .LBB0_848
	v_add_u32_e32 v162, 47, v240
	v_cmp_lt_u32_e32 vcc, s95, v162
	v_add_u32_e32 v162, 46, v240
	s_nop 0
	v_cndmask_b32_e32 v90, v243, v90, vcc
	v_cmp_lt_u32_e32 vcc, s95, v162
	v_add_u32_e32 v162, 45, v240
	s_nop 0
	v_cndmask_b32_e32 v91, v243, v91, vcc
	v_cmp_lt_u32_e32 vcc, s95, v162
	v_add_u32_e32 v162, 44, v240
	s_nop 0
	v_cndmask_b32_e32 v92, v243, v92, vcc
	v_cmp_lt_u32_e32 vcc, s95, v162
	s_nop 1
	v_cndmask_b32_e32 v93, v243, v93, vcc
.LBB0_848:
	v_max3_f32 v162, v174, v90, v91
	v_max3_f32 v162, v162, v92, v93
	s_waitcnt lgkmcnt(1)
	v_mfma_f32_32x32x16_bf16 v[18:33], v[170:173], v[178:181], v[18:33]
	ds_read2_b64 v[174:177], v208 offset0:40 offset1:42
	s_and_b64 vcc, exec, s[0:1]
	s_cbranch_vccnz .LBB0_850
	v_add_u32_e32 v163, 39, v240
	v_cmp_lt_u32_e32 vcc, s95, v163
	v_add_u32_e32 v163, 38, v240
	s_nop 0
	v_cndmask_b32_e32 v94, v243, v94, vcc
	v_cmp_lt_u32_e32 vcc, s95, v163
	v_add_u32_e32 v163, 37, v240
	s_nop 0
	v_cndmask_b32_e32 v95, v243, v95, vcc
	v_cmp_lt_u32_e32 vcc, s95, v163
	v_add_u32_e32 v163, 36, v240
	s_nop 0
	v_cndmask_b32_e32 v96, v243, v96, vcc
	v_cmp_lt_u32_e32 vcc, s95, v163
	s_nop 1
	v_cndmask_b32_e32 v97, v243, v97, vcc
.LBB0_850:
	v_exp_f32_e32 v178, v66
	v_exp_f32_e32 v179, v67
	v_exp_f32_e32 v180, v68
	v_exp_f32_e32 v181, v69
	v_exp_f32_e32 v220, v70
	v_exp_f32_e32 v221, v71
	v_exp_f32_e32 v222, v72
	v_exp_f32_e32 v223, v73
	v_cvt_pk_bf16_f32 v170, v178, v179
	v_cvt_pk_bf16_f32 v171, v180, v181
	v_cvt_pk_bf16_f32 v172, v220, v221
	v_cvt_pk_bf16_f32 v173, v222, v223
	v_max3_f32 v162, v162, v94, v95
	v_max3_f32 v225, v162, v96, v97
	s_waitcnt lgkmcnt(1)
	v_mfma_f32_32x32x16_bf16 v[2:17], v[166:169], v[170:173], v[2:17]
	ds_read2_b64 v[162:165], v224 offset0:12 offset1:14
	s_and_b64 vcc, exec, s[0:1]
	s_cbranch_vccnz .LBB0_852
	v_add_u32_e32 v166, 31, v240
	v_cmp_lt_u32_e32 vcc, s95, v166
	v_add_u32_e32 v166, 30, v240
	s_nop 0
	v_cndmask_b32_e32 v98, v243, v98, vcc
	v_cmp_lt_u32_e32 vcc, s95, v166
	v_add_u32_e32 v166, 29, v240
	s_nop 0
	v_cndmask_b32_e32 v99, v243, v99, vcc
	v_cmp_lt_u32_e32 vcc, s95, v166
	v_add_u32_e32 v166, 28, v240
	s_nop 0
	v_cndmask_b32_e32 v100, v243, v100, vcc
	v_cmp_lt_u32_e32 vcc, s95, v166
	s_nop 1
	v_cndmask_b32_e32 v101, v243, v101, vcc
.LBB0_852:
	v_max3_f32 v166, v225, v98, v99
	v_max3_f32 v228, v166, v100, v101
	s_waitcnt lgkmcnt(1)
	v_mfma_f32_32x32x16_bf16 v[18:33], v[174:177], v[170:173], v[18:33]
	ds_read2_b64 v[166:169], v208 offset0:44 offset1:46
	s_and_b64 vcc, exec, s[0:1]
	s_cbranch_vccnz .LBB0_854
	v_add_u32_e32 v170, 23, v240
	v_cmp_lt_u32_e32 vcc, s95, v170
	v_add_u32_e32 v170, 22, v240
	s_nop 0
	v_cndmask_b32_e32 v102, v243, v102, vcc
	v_cmp_lt_u32_e32 vcc, s95, v170
	v_add_u32_e32 v170, 21, v240
	s_nop 0
	v_cndmask_b32_e32 v103, v243, v103, vcc
	v_cmp_lt_u32_e32 vcc, s95, v170
	v_add_u32_e32 v170, 20, v240
	s_nop 0
	v_cndmask_b32_e32 v104, v243, v104, vcc
	v_cmp_lt_u32_e32 vcc, s95, v170
	s_nop 1
	v_cndmask_b32_e32 v105, v243, v105, vcc
.LBB0_854:
	v_exp_f32_e32 v176, v74
	v_exp_f32_e32 v177, v75
	v_exp_f32_e32 v226, v76
	v_exp_f32_e32 v227, v77
	v_exp_f32_e32 v174, v78
	v_exp_f32_e32 v175, v79
	v_exp_f32_e32 v224, v80
	v_exp_f32_e32 v225, v81
	v_cvt_pk_bf16_f32 v170, v176, v177
	v_cvt_pk_bf16_f32 v171, v226, v227
	v_cvt_pk_bf16_f32 v172, v174, v175
	v_cvt_pk_bf16_f32 v173, v224, v225
	v_max3_f32 v208, v228, v102, v103
	v_max3_f32 v208, v208, v104, v105
	s_waitcnt lgkmcnt(1)
	v_mfma_f32_32x32x16_bf16 v[2:17], v[162:165], v[170:173], v[2:17]
	s_and_b64 vcc, exec, s[0:1]
	s_cbranch_vccnz .LBB0_856
	v_add_u32_e32 v162, 15, v240
	v_cmp_lt_u32_e32 vcc, s95, v162
	v_add_u32_e32 v162, 14, v240
	s_nop 0
	v_cndmask_b32_e32 v106, v243, v106, vcc
	v_cmp_lt_u32_e32 vcc, s95, v162
	v_add_u32_e32 v162, 13, v240
	s_nop 0
	v_cndmask_b32_e32 v107, v243, v107, vcc
	v_cmp_lt_u32_e32 vcc, s95, v162
	v_add_u32_e32 v162, 12, v240
	s_nop 0
	v_cndmask_b32_e32 v108, v243, v108, vcc
	v_cmp_lt_u32_e32 vcc, s95, v162
	s_nop 1
	v_cndmask_b32_e32 v109, v243, v109, vcc
.LBB0_856:
	v_max3_f32 v162, v208, v106, v107
	v_max3_f32 v162, v162, v108, v109
	s_waitcnt lgkmcnt(0)
	v_mfma_f32_32x32x16_bf16 v[18:33], v[166:169], v[170:173], v[18:33]
	s_and_b64 vcc, exec, s[0:1]
	s_cbranch_vccnz .LBB0_858
	v_add_u32_e32 v163, 7, v240
	v_cmp_lt_u32_e32 vcc, s95, v163
	v_add_u32_e32 v163, 6, v240
	s_nop 0
	v_cndmask_b32_e32 v110, v243, v110, vcc
	v_cmp_lt_u32_e32 vcc, s95, v163
	v_add_u32_e32 v163, 5, v240
	s_nop 0
	v_cndmask_b32_e32 v111, v243, v111, vcc
	v_cmp_lt_u32_e32 vcc, s95, v163
	v_add_u32_e32 v163, 4, v240
	s_nop 0
	v_cndmask_b32_e32 v112, v243, v112, vcc
	v_cmp_lt_u32_e32 vcc, s95, v163
	s_nop 1
	v_cndmask_b32_e32 v113, v243, v113, vcc

.LBB0_863:
	v_max3_f32 v174, v231, v34, v35
	v_max3_f32 v220, v174, v36, v37
	s_waitcnt lgkmcnt(1)
	v_mfma_f32_32x32x16_bf16 v[18:33], v[170:173], v[162:165], v[18:33]
	ds_read2_b64 v[174:177], v208 offset0:36 offset1:38
	s_and_b64 vcc, exec, s[0:1]
	s_cbranch_vccnz .LBB0_865
	v_add_u32_e32 v162, -9, v240
	v_cmp_lt_u32_e32 vcc, s95, v162
	v_add_u32_e32 v162, -10, v240
	s_nop 0
	v_cndmask_b32_e32 v38, v243, v38, vcc
	v_cmp_lt_u32_e32 vcc, s95, v162
	v_add_u32_e32 v162, -11, v240
	s_nop 0
	v_cndmask_b32_e32 v39, v243, v39, vcc
	v_cmp_lt_u32_e32 vcc, s95, v162
	v_add_u32_e32 v162, -12, v240
	s_nop 0
	v_cndmask_b32_e32 v40, v243, v40, vcc
	v_cmp_lt_u32_e32 vcc, s95, v162
	s_nop 1
	v_cndmask_b32_e32 v41, v243, v41, vcc
.LBB0_865:
	v_exp_f32_e32 v204, v90
	v_exp_f32_e32 v205, v91
	v_exp_f32_e32 v214, v92
	v_exp_f32_e32 v215, v93
	v_exp_f32_e32 v216, v94
	v_exp_f32_e32 v217, v95
	v_exp_f32_e32 v218, v96
	v_exp_f32_e32 v219, v97
	v_cvt_pk_bf16_f32 v178, v204, v205
	v_cvt_pk_bf16_f32 v179, v214, v215
	v_cvt_pk_bf16_f32 v180, v216, v217
	v_cvt_pk_bf16_f32 v181, v218, v219
	v_max3_f32 v162, v220, v38, v39
	v_max3_f32 v170, v162, v40, v41
	s_waitcnt lgkmcnt(1)
	v_mfma_f32_32x32x16_bf16 v[2:17], v[166:169], v[178:181], v[2:17]
	ds_read2_b64 v[162:165], v224 offset0:8 offset1:10
	s_and_b64 vcc, exec, s[0:1]
	s_cbranch_vccnz .LBB0_867
	v_subrev_u32_e32 v166, 17, v240
	v_cmp_lt_u32_e32 vcc, s95, v166
	v_subrev_u32_e32 v166, 18, v240
	s_nop 0
	v_cndmask_b32_e32 v42, v243, v42, vcc
	v_cmp_lt_u32_e32 vcc, s95, v166
	v_subrev_u32_e32 v166, 19, v240
	s_nop 0
	v_cndmask_b32_e32 v43, v243, v43, vcc
	v_cmp_lt_u32_e32 vcc, s95, v166
	v_subrev_u32_e32 v166, 20, v240
	s_nop 0
	v_cndmask_b32_e32 v44, v243, v44, vcc
	v_cmp_lt_u32_e32 vcc, s95, v166
	s_nop 1
	v_cndmask_b32_e32 v45, v243, v45, vcc
.LBB0_867:
	v_max3_f32 v166, v170, v42, v43
	v_max3_f32 v166, v166, v44, v45
	s_waitcnt lgkmcnt(1)
	v_mfma_f32_32x32x16_bf16 v[18:33], v[174:177], v[178:181], v[18:33]
	ds_read2_b64 v[170:173], v208 offset0:40 offset1:42
	s_and_b64 vcc, exec, s[0:1]
	s_cbranch_vccnz .LBB0_869
	v_subrev_u32_e32 v167, 25, v240
	v_cmp_lt_u32_e32 vcc, s95, v167
	v_subrev_u32_e32 v167, 26, v240
	s_nop 0
	v_cndmask_b32_e32 v46, v243, v46, vcc
	v_cmp_lt_u32_e32 vcc, s95, v167
	v_subrev_u32_e32 v167, 27, v240
	s_nop 0
	v_cndmask_b32_e32 v47, v243, v47, vcc
	v_cmp_lt_u32_e32 vcc, s95, v167
	v_subrev_u32_e32 v167, 28, v240
	s_nop 0
	v_cndmask_b32_e32 v48, v243, v48, vcc
	v_cmp_lt_u32_e32 vcc, s95, v167
	s_nop 1
	v_cndmask_b32_e32 v49, v243, v49, vcc
.LBB0_869:
	v_exp_f32_e32 v178, v98
	v_exp_f32_e32 v179, v99
	v_exp_f32_e32 v180, v100
	v_exp_f32_e32 v181, v101
	v_exp_f32_e32 v220, v102
	v_exp_f32_e32 v221, v103
	v_exp_f32_e32 v222, v104
	v_exp_f32_e32 v223, v105
	v_cvt_pk_bf16_f32 v174, v178, v179
	v_cvt_pk_bf16_f32 v175, v180, v181
	v_cvt_pk_bf16_f32 v176, v220, v221
	v_cvt_pk_bf16_f32 v177, v222, v223
	v_max3_f32 v166, v166, v46, v47
	v_max3_f32 v225, v166, v48, v49
	s_waitcnt lgkmcnt(1)
	v_mfma_f32_32x32x16_bf16 v[2:17], v[162:165], v[174:177], v[2:17]
	ds_read2_b64 v[166:169], v224 offset0:12 offset1:14
	s_and_b64 vcc, exec, s[0:1]
	s_cbranch_vccnz .LBB0_871
	v_subrev_u32_e32 v162, 33, v240
	v_cmp_lt_u32_e32 vcc, s95, v162
	v_subrev_u32_e32 v162, 34, v240
	s_nop 0
	v_cndmask_b32_e32 v66, v243, v66, vcc
	v_cmp_lt_u32_e32 vcc, s95, v162
	v_subrev_u32_e32 v162, 35, v240
	s_nop 0
	v_cndmask_b32_e32 v67, v243, v67, vcc
	v_cmp_lt_u32_e32 vcc, s95, v162
	v_subrev_u32_e32 v162, 36, v240
	s_nop 0
	v_cndmask_b32_e32 v68, v243, v68, vcc
	v_cmp_lt_u32_e32 vcc, s95, v162
	s_nop 1
	v_cndmask_b32_e32 v69, v243, v69, vcc
.LBB0_871:
	v_max3_f32 v162, v225, v66, v67
	v_max3_f32 v228, v162, v68, v69
	s_waitcnt lgkmcnt(1)
	v_mfma_f32_32x32x16_bf16 v[18:33], v[170:173], v[174:177], v[18:33]
	ds_read2_b64 v[162:165], v208 offset0:44 offset1:46
	s_and_b64 vcc, exec, s[0:1]
	s_cbranch_vccnz .LBB0_873
	v_subrev_u32_e32 v170, 41, v240
	v_cmp_lt_u32_e32 vcc, s95, v170
	v_subrev_u32_e32 v170, 42, v240
	s_nop 0
	v_cndmask_b32_e32 v70, v243, v70, vcc
	v_cmp_lt_u32_e32 vcc, s95, v170
	v_subrev_u32_e32 v170, 43, v240
	s_nop 0
	v_cndmask_b32_e32 v71, v243, v71, vcc
	v_cmp_lt_u32_e32 vcc, s95, v170
	v_subrev_u32_e32 v170, 44, v240
	s_nop 0
	v_cndmask_b32_e32 v72, v243, v72, vcc
	v_cmp_lt_u32_e32 vcc, s95, v170
	s_nop 1
	v_cndmask_b32_e32 v73, v243, v73, vcc
.LBB0_873:
	v_exp_f32_e32 v176, v106
	v_exp_f32_e32 v177, v107
	v_exp_f32_e32 v226, v108
	v_exp_f32_e32 v227, v109
	v_exp_f32_e32 v174, v110
	v_exp_f32_e32 v175, v111
	v_exp_f32_e32 v224, v112
	v_exp_f32_e32 v225, v113
	v_cvt_pk_bf16_f32 v170, v176, v177
	v_cvt_pk_bf16_f32 v171, v226, v227
	v_cvt_pk_bf16_f32 v172, v174, v175
	v_cvt_pk_bf16_f32 v173, v224, v225
	v_max3_f32 v208, v228, v70, v71
	v_max3_f32 v208, v208, v72, v73
	s_waitcnt lgkmcnt(1)
	v_mfma_f32_32x32x16_bf16 v[2:17], v[166:169], v[170:173], v[2:17]
	s_and_b64 vcc, exec, s[0:1]
	s_cbranch_vccnz .LBB0_875
	v_subrev_u32_e32 v166, 49, v240
	v_cmp_lt_u32_e32 vcc, s95, v166
	v_subrev_u32_e32 v166, 50, v240
	s_nop 0
	v_cndmask_b32_e32 v74, v243, v74, vcc
	v_cmp_lt_u32_e32 vcc, s95, v166
	v_subrev_u32_e32 v166, 51, v240
	s_nop 0
	v_cndmask_b32_e32 v75, v243, v75, vcc
	v_cmp_lt_u32_e32 vcc, s95, v166
	v_subrev_u32_e32 v166, 52, v240
	s_nop 0
	v_cndmask_b32_e32 v76, v243, v76, vcc
	v_cmp_lt_u32_e32 vcc, s95, v166
	s_nop 1
	v_cndmask_b32_e32 v77, v243, v77, vcc
.LBB0_875:
	v_max3_f32 v166, v208, v74, v75
	v_max3_f32 v166, v166, v76, v77
	s_waitcnt lgkmcnt(0)
	v_mfma_f32_32x32x16_bf16 v[18:33], v[162:165], v[170:173], v[18:33]
	s_and_b64 vcc, exec, s[0:1]
	s_cbranch_vccnz .LBB0_877
	v_subrev_u32_e32 v162, 57, v240
	v_cmp_lt_u32_e32 vcc, s95, v162
	v_subrev_u32_e32 v162, 58, v240
	s_nop 0
	v_cndmask_b32_e32 v78, v243, v78, vcc
	v_cmp_lt_u32_e32 vcc, s95, v162
	v_subrev_u32_e32 v162, 59, v240
	s_nop 0
	v_cndmask_b32_e32 v79, v243, v79, vcc
	v_cmp_lt_u32_e32 vcc, s95, v162
	v_subrev_u32_e32 v162, 60, v240
	s_nop 0
	v_cndmask_b32_e32 v80, v243, v80, vcc
	v_cmp_lt_u32_e32 vcc, s95, v162
	s_nop 1
	v_cndmask_b32_e32 v81, v243, v81, vcc

.LBB0_884:
	v_max3_f32 v174, v231, v82, v83
	v_max3_f32 v220, v174, v84, v85
	s_waitcnt lgkmcnt(1)
	v_mfma_f32_32x32x16_bf16 v[18:33], v[170:173], v[162:165], v[18:33]
	ds_read2_b64 v[174:177], v208 offset0:36 offset1:38
	s_and_b64 vcc, exec, s[0:1]
	s_cbranch_vccnz .LBB0_886
	v_add_u32_e32 v162, 0xffffffb7, v240
	v_cmp_lt_u32_e32 vcc, s95, v162
	v_add_u32_e32 v162, 0xffffffb6, v240
	s_nop 0
	v_cndmask_b32_e32 v86, v243, v86, vcc
	v_cmp_lt_u32_e32 vcc, s95, v162
	v_add_u32_e32 v162, 0xffffffb5, v240
	s_nop 0
	v_cndmask_b32_e32 v87, v243, v87, vcc
	v_cmp_lt_u32_e32 vcc, s95, v162
	v_add_u32_e32 v162, 0xffffffb4, v240
	s_nop 0
	v_cndmask_b32_e32 v88, v243, v88, vcc
	v_cmp_lt_u32_e32 vcc, s95, v162
	s_nop 1
	v_cndmask_b32_e32 v89, v243, v89, vcc
.LBB0_886:
	v_exp_f32_e32 v204, v42
	v_exp_f32_e32 v205, v43
	v_exp_f32_e32 v214, v44
	v_exp_f32_e32 v215, v45
	v_exp_f32_e32 v216, v46
	v_exp_f32_e32 v217, v47
	v_exp_f32_e32 v218, v48
	v_exp_f32_e32 v219, v49
	v_cvt_pk_bf16_f32 v178, v204, v205
	v_cvt_pk_bf16_f32 v179, v214, v215
	v_cvt_pk_bf16_f32 v180, v216, v217
	v_cvt_pk_bf16_f32 v181, v218, v219
	v_max3_f32 v162, v220, v86, v87
	v_max3_f32 v170, v162, v88, v89
	s_waitcnt lgkmcnt(1)
	v_mfma_f32_32x32x16_bf16 v[2:17], v[166:169], v[178:181], v[2:17]
	ds_read2_b64 v[162:165], v224 offset0:8 offset1:10
	s_and_b64 vcc, exec, s[0:1]
	s_cbranch_vccnz .LBB0_888
	v_add_u32_e32 v166, 0xffffffaf, v240
	v_cmp_lt_u32_e32 vcc, s95, v166
	v_add_u32_e32 v166, 0xffffffae, v240
	s_nop 0
	v_cndmask_b32_e32 v90, v243, v90, vcc
	v_cmp_lt_u32_e32 vcc, s95, v166
	v_add_u32_e32 v166, 0xffffffad, v240
	s_nop 0
	v_cndmask_b32_e32 v91, v243, v91, vcc
	v_cmp_lt_u32_e32 vcc, s95, v166
	v_add_u32_e32 v166, 0xffffffac, v240
	s_nop 0
	v_cndmask_b32_e32 v92, v243, v92, vcc
	v_cmp_lt_u32_e32 vcc, s95, v166
	s_nop 1
	v_cndmask_b32_e32 v93, v243, v93, vcc
.LBB0_888:
	v_max3_f32 v166, v170, v90, v91
	v_max3_f32 v166, v166, v92, v93
	s_waitcnt lgkmcnt(1)
	v_mfma_f32_32x32x16_bf16 v[18:33], v[174:177], v[178:181], v[18:33]
	ds_read2_b64 v[170:173], v208 offset0:40 offset1:42
	s_and_b64 vcc, exec, s[0:1]
	s_cbranch_vccnz .LBB0_890
	v_add_u32_e32 v167, 0xffffffa7, v240
	v_cmp_lt_u32_e32 vcc, s95, v167
	v_add_u32_e32 v167, 0xffffffa6, v240
	s_nop 0
	v_cndmask_b32_e32 v94, v243, v94, vcc
	v_cmp_lt_u32_e32 vcc, s95, v167
	v_add_u32_e32 v167, 0xffffffa5, v240
	s_nop 0
	v_cndmask_b32_e32 v95, v243, v95, vcc
	v_cmp_lt_u32_e32 vcc, s95, v167
	v_add_u32_e32 v167, 0xffffffa4, v240
	s_nop 0
	v_cndmask_b32_e32 v96, v243, v96, vcc
	v_cmp_lt_u32_e32 vcc, s95, v167
	s_nop 1
	v_cndmask_b32_e32 v97, v243, v97, vcc
.LBB0_890:
	v_exp_f32_e32 v178, v66
	v_exp_f32_e32 v179, v67
	v_exp_f32_e32 v180, v68
	v_exp_f32_e32 v181, v69
	v_exp_f32_e32 v220, v70
	v_exp_f32_e32 v221, v71
	v_exp_f32_e32 v222, v72
	v_exp_f32_e32 v223, v73
	v_cvt_pk_bf16_f32 v174, v178, v179
	v_cvt_pk_bf16_f32 v175, v180, v181
	v_cvt_pk_bf16_f32 v176, v220, v221
	v_cvt_pk_bf16_f32 v177, v222, v223
	v_max3_f32 v166, v166, v94, v95
	v_max3_f32 v225, v166, v96, v97
	s_waitcnt lgkmcnt(1)
	v_mfma_f32_32x32x16_bf16 v[2:17], v[162:165], v[174:177], v[2:17]
	ds_read2_b64 v[166:169], v224 offset0:12 offset1:14
	s_and_b64 vcc, exec, s[0:1]
	s_cbranch_vccnz .LBB0_892
	v_add_u32_e32 v162, 0xffffff9f, v240
	v_cmp_lt_u32_e32 vcc, s95, v162
	v_add_u32_e32 v162, 0xffffff9e, v240
	s_nop 0
	v_cndmask_b32_e32 v98, v243, v98, vcc
	v_cmp_lt_u32_e32 vcc, s95, v162
	v_add_u32_e32 v162, 0xffffff9d, v240
	s_nop 0
	v_cndmask_b32_e32 v99, v243, v99, vcc
	v_cmp_lt_u32_e32 vcc, s95, v162
	v_add_u32_e32 v162, 0xffffff9c, v240
	s_nop 0
	v_cndmask_b32_e32 v100, v243, v100, vcc
	v_cmp_lt_u32_e32 vcc, s95, v162
	s_nop 1
	v_cndmask_b32_e32 v101, v243, v101, vcc
.LBB0_892:
	v_max3_f32 v162, v225, v98, v99
	v_max3_f32 v228, v162, v100, v101
	s_waitcnt lgkmcnt(1)
	v_mfma_f32_32x32x16_bf16 v[18:33], v[170:173], v[174:177], v[18:33]
	ds_read2_b64 v[162:165], v208 offset0:44 offset1:46
	s_and_b64 vcc, exec, s[0:1]
	s_cbranch_vccnz .LBB0_894
	v_add_u32_e32 v170, 0xffffff97, v240
	v_cmp_lt_u32_e32 vcc, s95, v170
	v_add_u32_e32 v170, 0xffffff96, v240
	s_nop 0
	v_cndmask_b32_e32 v102, v243, v102, vcc
	v_cmp_lt_u32_e32 vcc, s95, v170
	v_add_u32_e32 v170, 0xffffff95, v240
	s_nop 0
	v_cndmask_b32_e32 v103, v243, v103, vcc
	v_cmp_lt_u32_e32 vcc, s95, v170
	v_add_u32_e32 v170, 0xffffff94, v240
	s_nop 0
	v_cndmask_b32_e32 v104, v243, v104, vcc
	v_cmp_lt_u32_e32 vcc, s95, v170
	s_nop 1
	v_cndmask_b32_e32 v105, v243, v105, vcc
.LBB0_894:
	v_exp_f32_e32 v176, v74
	v_exp_f32_e32 v177, v75
	v_exp_f32_e32 v226, v76
	v_exp_f32_e32 v227, v77
	v_exp_f32_e32 v174, v78
	v_exp_f32_e32 v175, v79
	v_exp_f32_e32 v224, v80
	v_exp_f32_e32 v225, v81
	v_cvt_pk_bf16_f32 v170, v176, v177
	v_cvt_pk_bf16_f32 v171, v226, v227
	v_cvt_pk_bf16_f32 v172, v174, v175
	v_cvt_pk_bf16_f32 v173, v224, v225
	v_max3_f32 v208, v228, v102, v103
	v_max3_f32 v208, v208, v104, v105
	s_waitcnt lgkmcnt(1)
	v_mfma_f32_32x32x16_bf16 v[2:17], v[166:169], v[170:173], v[2:17]
	s_and_b64 vcc, exec, s[0:1]
	s_cbranch_vccnz .LBB0_896
	v_add_u32_e32 v166, 0xffffff8f, v240
	v_cmp_lt_u32_e32 vcc, s95, v166
	v_add_u32_e32 v166, 0xffffff8e, v240
	s_nop 0
	v_cndmask_b32_e32 v106, v243, v106, vcc
	v_cmp_lt_u32_e32 vcc, s95, v166
	v_add_u32_e32 v166, 0xffffff8d, v240
	s_nop 0
	v_cndmask_b32_e32 v107, v243, v107, vcc
	v_cmp_lt_u32_e32 vcc, s95, v166
	v_add_u32_e32 v166, 0xffffff8c, v240
	s_nop 0
	v_cndmask_b32_e32 v108, v243, v108, vcc
	v_cmp_lt_u32_e32 vcc, s95, v166
	s_nop 1
	v_cndmask_b32_e32 v109, v243, v109, vcc
.LBB0_896:
	v_max3_f32 v166, v208, v106, v107
	v_max3_f32 v166, v166, v108, v109
	s_waitcnt lgkmcnt(0)
	v_mfma_f32_32x32x16_bf16 v[18:33], v[162:165], v[170:173], v[18:33]
	s_and_b64 vcc, exec, s[0:1]
	s_cbranch_vccnz .LBB0_898
	v_add_u32_e32 v162, 0xffffff87, v240
	v_cmp_lt_u32_e32 vcc, s95, v162
	v_add_u32_e32 v162, 0xffffff86, v240
	s_nop 0
	v_cndmask_b32_e32 v110, v243, v110, vcc
	v_cmp_lt_u32_e32 vcc, s95, v162
	v_add_u32_e32 v162, 0xffffff85, v240
	s_nop 0
	v_cndmask_b32_e32 v111, v243, v111, vcc
	v_cmp_lt_u32_e32 vcc, s95, v162
	v_add_u32_e32 v162, 0xffffff84, v240
	s_nop 0
	v_cndmask_b32_e32 v112, v243, v112, vcc
	v_cmp_lt_u32_e32 vcc, s95, v162
	s_nop 1
	v_cndmask_b32_e32 v113, v243, v113, vcc

.LBB0_926:
	s_or_b64 exec, exec, s[6:7]
	v_lshlrev_b32_e32 v2, 3, v248
	v_add_co_u32_e32 v4, vcc, 0xc000, v220
	v_lshl_add_u32 v3, v2, 1, 0
	s_movk_i32 s4, 0xd0
	v_addc_co_u32_e32 v5, vcc, 0, v221, vcc
	v_mad_u32_u24 v8, v247, s4, v3
	global_load_dwordx4 v[202:205], v[4:5], off
	s_waitcnt lgkmcnt(0)
	s_barrier
	ds_read_b128 v[4:7], v8
	v_readlane_b32 s68, v254, 41
	v_readlane_b32 s69, v254, 42
	v_readlane_b32 s70, v254, 43
	v_readlane_b32 s71, v254, 44
	v_readlane_b32 s72, v254, 45
	v_readlane_b32 s73, v254, 46
	v_readlane_b32 s74, v254, 47
	v_readlane_b32 s75, v254, 48
	v_readlane_b32 s76, v254, 49
	v_readlane_b32 s77, v254, 50
	v_readlane_b32 s78, v254, 51
	v_readlane_b32 s79, v254, 52
	v_readlane_b32 s80, v254, 53
	v_readlane_b32 s81, v254, 54
	v_readlane_b32 s82, v254, 55
	v_readlane_b32 s83, v254, 56
	s_mov_b32 s69, s68
	s_mov_b32 s70, s68
	s_mov_b32 s71, s68
	s_mov_b32 s72, s68
	s_mov_b32 s73, s68
	s_mov_b32 s74, s68
	s_mov_b32 s75, s68
	s_mov_b32 s76, s68
	s_mov_b32 s77, s68
	s_mov_b32 s78, s68
	s_mov_b32 s79, s68
	s_mov_b32 s80, s68
	s_mov_b32 s81, s68
	s_mov_b32 s82, s68
	s_mov_b32 s83, s68
	v_mov_b64_e32 v[34:35], s[68:69]
	v_mov_b64_e32 v[36:37], s[70:71]
	v_mov_b64_e32 v[38:39], s[72:73]
	v_mov_b64_e32 v[40:41], s[74:75]
	v_mov_b64_e32 v[42:43], s[76:77]
	v_mov_b64_e32 v[44:45], s[78:79]
	v_mov_b64_e32 v[46:47], s[80:81]
	v_mov_b64_e32 v[48:49], s[82:83]
	v_mad_u32_u24 v3, v249, s4, v3
	s_mov_b32 s16, s68
	s_waitcnt lgkmcnt(0)
	v_mfma_f32_32x32x16_bf16 v[66:81], v[4:7], v[134:137], v[34:49]
	ds_read_b128 v[4:7], v8 offset:32
	v_writelane_b32 v254, s16, 41
	v_mov_b32_e32 v223, 0xf149f2ca
	s_nop 0
	v_writelane_b32 v254, s17, 42
	v_writelane_b32 v254, s18, 43
	v_writelane_b32 v254, s19, 44
	s_waitcnt lgkmcnt(0)
	v_mfma_f32_32x32x16_bf16 v[66:81], v[4:7], v[138:141], v[66:81]
	ds_read_b128 v[4:7], v8 offset:64
	v_writelane_b32 v254, s20, 45
	v_writelane_b32 v254, s21, 46
	v_writelane_b32 v254, s22, 47
	v_writelane_b32 v254, s23, 48
	v_writelane_b32 v254, s24, 49
	v_writelane_b32 v254, s25, 50
	s_waitcnt lgkmcnt(0)
	v_mfma_f32_32x32x16_bf16 v[66:81], v[4:7], v[142:145], v[66:81]
	ds_read_b128 v[4:7], v8 offset:96
	v_writelane_b32 v254, s26, 51
	v_writelane_b32 v254, s27, 52
	v_writelane_b32 v254, s28, 53
	v_writelane_b32 v254, s29, 54
	v_writelane_b32 v254, s30, 55
	v_writelane_b32 v254, s31, 56
	s_waitcnt lgkmcnt(0)
	v_mfma_f32_32x32x16_bf16 v[66:81], v[4:7], v[146:149], v[66:81]
	ds_read_b128 v[4:7], v8 offset:128
	s_waitcnt lgkmcnt(0)
	v_mfma_f32_32x32x16_bf16 v[66:81], v[4:7], v[150:153], v[66:81]
	ds_read_b128 v[4:7], v8 offset:160
	s_waitcnt lgkmcnt(0)
	v_mfma_f32_32x32x16_bf16 v[66:81], v[4:7], v[154:157], v[66:81]
	ds_read_b128 v[4:7], v3
	s_waitcnt lgkmcnt(0)
	v_mfma_f32_32x32x16_bf16 v[34:49], v[4:7], v[134:137], v[34:49]
	ds_read_b128 v[4:7], v3 offset:32
	s_waitcnt lgkmcnt(0)
	v_mfma_f32_32x32x16_bf16 v[34:49], v[4:7], v[138:141], v[34:49]
	ds_read_b128 v[4:7], v3 offset:64
	s_waitcnt lgkmcnt(0)
	v_mfma_f32_32x32x16_bf16 v[34:49], v[4:7], v[142:145], v[34:49]
	ds_read_b128 v[4:7], v3 offset:96
	s_waitcnt lgkmcnt(0)
	v_mfma_f32_32x32x16_bf16 v[34:49], v[4:7], v[146:149], v[34:49]
	ds_read_b128 v[4:7], v3 offset:128
	s_waitcnt lgkmcnt(0)
	v_mfma_f32_32x32x16_bf16 v[34:49], v[4:7], v[150:153], v[34:49]
	ds_read_b128 v[4:7], v3 offset:160
	s_waitcnt lgkmcnt(0)
	v_mfma_f32_32x32x16_bf16 v[34:49], v[4:7], v[154:157], v[34:49]
	v_max3_f32 v3, v66, v67, v34
	v_max3_f32 v3, v3, v68, v69
	s_nop 10
	v_max_f32_e32 v4, v35, v35
	v_max3_f32 v3, v3, v70, v71
	v_max3_f32 v3, v3, v72, v73
	v_max3_f32 v3, v3, v74, v75
	v_max3_f32 v3, v3, v76, v77
	v_max3_f32 v3, v3, v78, v79
	v_max3_f32 v3, v3, v80, v81
	v_max3_f32 v3, v3, v36, v37
	v_max3_f32 v3, v3, v38, v39
	v_max3_f32 v3, v3, v40, v41
	v_max3_f32 v3, v3, v42, v43
	v_max3_f32 v3, v3, v44, v45
	v_max3_f32 v3, v3, v46, v47
	v_max3_f32 v3, v3, v48, v49
	s_nop 0
	v_max_f32_e32 v3, v3, v3
	v_max_f32_e32 v3, v3, v4
	v_cmp_gt_f32_e32 vcc, v3, v223
	s_cbranch_vccz .LBB0_930
	v_cmp_lt_i32_e32 vcc, v241, v235
	s_nop 1
	v_cndmask_b32_e32 v4, v233, v241, vcc
	v_lshlrev_b32_e32 v4, 2, v4
	ds_bpermute_b32 v4, v4, v3
	v_max_f32_e32 v3, v3, v3
	s_waitcnt lgkmcnt(0)
	v_max_f32_e32 v4, v4, v4
	v_max_f32_e32 v3, v3, v4
	v_add_f32_e32 v3, 0, v3
	v_max_f32_e32 v222, 0xf149f2ca, v3
	v_sub_f32_e32 v3, 0xf149f2ca, v222
	v_exp_f32_e32 v3, v3
	v_sub_f32_e32 v4, 0, v222
	v_pk_add_f32 v[80:81], v[80:81], v[4:5] op_sel_hi:[1,0]
	v_pk_add_f32 v[78:79], v[78:79], v[4:5] op_sel_hi:[1,0]
	v_pk_add_f32 v[76:77], v[76:77], v[4:5] op_sel_hi:[1,0]
	v_pk_add_f32 v[74:75], v[74:75], v[4:5] op_sel_hi:[1,0]
	v_mul_f32_e32 v98, 0, v3
	v_pk_add_f32 v[72:73], v[72:73], v[4:5] op_sel_hi:[1,0]
	v_pk_add_f32 v[70:71], v[70:71], v[4:5] op_sel_hi:[1,0]
	v_pk_add_f32 v[68:69], v[68:69], v[4:5] op_sel_hi:[1,0]
	v_pk_add_f32 v[66:67], v[66:67], v[4:5] op_sel_hi:[1,0]
	v_pk_add_f32 v[48:49], v[48:49], v[4:5] op_sel_hi:[1,0]
	v_pk_add_f32 v[46:47], v[46:47], v[4:5] op_sel_hi:[1,0]
	v_pk_add_f32 v[44:45], v[44:45], v[4:5] op_sel_hi:[1,0]
	v_pk_add_f32 v[42:43], v[42:43], v[4:5] op_sel_hi:[1,0]
	v_pk_add_f32 v[40:41], v[40:41], v[4:5] op_sel_hi:[1,0]
	v_pk_add_f32 v[38:39], v[38:39], v[4:5] op_sel_hi:[1,0]
	v_pk_add_f32 v[36:37], v[36:37], v[4:5] op_sel_hi:[1,0]
	v_pk_add_f32 v[34:35], v[34:35], v[4:5] op_sel_hi:[1,0]
	v_xor_b32_e32 v50, 0x80000000, v222
	v_mov_b32_e32 v223, v222
	s_branch .LBB0_931

.LBB0_937:
	s_or_b64 exec, exec, s[6:7]
	s_lshl_b32 s84, s14, 7
	v_lshl_add_u64 v[82:83], v[220:221], 0, s[84:85]
	global_load_dwordx4 v[178:181], v[82:83], off
	ds_read_b128 v[100:103], v249 offset:13312
	ds_read_b128 v[104:107], v249 offset:13344
	s_mul_i32 s4, s10, 0x2200
	v_add_u32_e32 v99, s4, v248
	s_waitcnt lgkmcnt(1)
	v_mfma_f32_32x32x16_bf16 v[82:97], v[100:103], v[134:137], v[50:65]
	v_exp_f32_e32 v100, v66
	v_exp_f32_e32 v101, v67
	ds_read_b128 v[108:111], v249 offset:13376
	v_exp_f32_e32 v68, v68
	v_exp_f32_e32 v69, v69
	v_cvt_pk_bf16_f32 v66, v100, v101
	v_cvt_pk_bf16_f32 v67, v68, v69
	v_pk_add_f32 v[112:113], v[68:69], v[100:101]
	s_waitcnt lgkmcnt(1)
	v_mfma_f32_32x32x16_bf16 v[82:97], v[104:107], v[138:141], v[82:97]
	ds_read_b128 v[100:103], v249 offset:13408
	v_exp_f32_e32 v70, v70
	v_exp_f32_e32 v71, v71
	v_exp_f32_e32 v72, v72
	v_exp_f32_e32 v73, v73
	v_cvt_pk_bf16_f32 v68, v70, v71
	v_pk_add_f32 v[70:71], v[70:71], v[112:113]
	v_cvt_pk_bf16_f32 v69, v72, v73
	v_pk_add_f32 v[112:113], v[72:73], v[70:71]
	s_waitcnt lgkmcnt(1)
	v_mfma_f32_32x32x16_bf16 v[82:97], v[108:111], v[142:145], v[82:97]
	v_exp_f32_e32 v72, v74
	v_exp_f32_e32 v73, v75
	ds_read_b128 v[104:107], v249 offset:13440
	v_exp_f32_e32 v74, v76
	v_exp_f32_e32 v75, v77
	v_cvt_pk_bf16_f32 v70, v72, v73
	v_pk_add_f32 v[72:73], v[72:73], v[112:113]
	v_cvt_pk_bf16_f32 v71, v74, v75
	v_pk_add_f32 v[108:109], v[74:75], v[72:73]
	s_waitcnt lgkmcnt(1)
	v_mfma_f32_32x32x16_bf16 v[82:97], v[100:103], v[146:149], v[82:97]
	v_exp_f32_e32 v78, v78
	v_exp_f32_e32 v79, v79
	v_exp_f32_e32 v80, v80
	v_exp_f32_e32 v81, v81
	ds_read_b128 v[74:77], v249 offset:13472
	v_cvt_pk_bf16_f32 v72, v78, v79
	v_pk_add_f32 v[78:79], v[78:79], v[108:109]
	v_cvt_pk_bf16_f32 v73, v80, v81
	v_pk_add_f32 v[100:101], v[80:81], v[78:79]
	s_waitcnt lgkmcnt(1)
	v_mfma_f32_32x32x16_bf16 v[82:97], v[104:107], v[150:153], v[82:97]
	v_exp_f32_e32 v34, v34
	v_exp_f32_e32 v35, v35
	ds_read_b128 v[78:81], v249 offset:19968
	v_pk_add_f32 v[104:105], v[34:35], v[100:101]
	v_cvt_pk_bf16_f32 v34, v34, v35
	s_waitcnt lgkmcnt(1)
	v_mfma_f32_32x32x16_bf16 v[82:97], v[74:77], v[154:157], v[82:97]
	v_exp_f32_e32 v36, v36
	v_exp_f32_e32 v37, v37
	ds_read_b128 v[100:103], v249 offset:20000
	v_pk_add_f32 v[104:105], v[36:37], v[104:105]
	v_cvt_pk_bf16_f32 v35, v36, v37
	s_waitcnt lgkmcnt(1)
	v_mfma_f32_32x32x16_bf16 v[118:133], v[78:81], v[134:137], v[50:65]
	v_exp_f32_e32 v36, v38
	v_exp_f32_e32 v37, v39
	ds_read_b128 v[74:77], v249 offset:20032
	v_pk_add_f32 v[38:39], v[36:37], v[104:105]
	v_cvt_pk_bf16_f32 v36, v36, v37
	s_waitcnt lgkmcnt(1)
	v_mfma_f32_32x32x16_bf16 v[118:133], v[100:103], v[138:141], v[118:133]
	v_exp_f32_e32 v40, v40
	v_exp_f32_e32 v41, v41
	ds_read_b128 v[78:81], v249 offset:20064
	v_pk_add_f32 v[38:39], v[40:41], v[38:39]
	v_cvt_pk_bf16_f32 v37, v40, v41
	s_waitcnt lgkmcnt(1)
	v_mfma_f32_32x32x16_bf16 v[118:133], v[74:77], v[142:145], v[118:133]
	v_exp_f32_e32 v40, v42
	v_exp_f32_e32 v41, v43
	ds_read_b128 v[100:103], v249 offset:20096
	v_pk_add_f32 v[42:43], v[40:41], v[38:39]
	v_cvt_pk_bf16_f32 v38, v40, v41
	s_waitcnt lgkmcnt(1)
	v_mfma_f32_32x32x16_bf16 v[118:133], v[78:81], v[146:149], v[118:133]
	v_exp_f32_e32 v40, v44
	v_exp_f32_e32 v41, v45
	ds_read_b128 v[74:77], v249 offset:20128
	v_pk_add_f32 v[42:43], v[40:41], v[42:43]
	v_cvt_pk_bf16_f32 v39, v40, v41
	s_waitcnt lgkmcnt(1)
	v_mfma_f32_32x32x16_bf16 v[118:133], v[100:103], v[150:153], v[118:133]
	v_add_u32_e32 v104, 0xd000, v99
	v_exp_f32_e32 v40, v46
	v_exp_f32_e32 v41, v47
	ds_read2_b64 v[78:81], v104 offset1:2
	v_pk_add_f32 v[42:43], v[40:41], v[42:43]
	v_cvt_pk_bf16_f32 v40, v40, v41
	s_waitcnt lgkmcnt(1)
	v_mfma_f32_32x32x16_bf16 v[118:133], v[74:77], v[154:157], v[118:133]
	v_add_u32_e32 v99, 0xe000, v99
	v_exp_f32_e32 v48, v48
	v_exp_f32_e32 v49, v49
	ds_read2_b64 v[44:47], v99 offset0:32 offset1:34
	v_pk_add_f32 v[42:43], v[48:49], v[42:43]
	v_cvt_pk_bf16_f32 v41, v48, v49
	s_setprio 1
	s_waitcnt lgkmcnt(1)
	v_mfma_f32_32x32x16_bf16 v[18:33], v[78:81], v[66:69], v[18:33]
	ds_read2_b64 v[74:77], v104 offset0:4 offset1:6
	v_max3_f32 v48, v231, v82, v83
	v_max3_f32 v48, v48, v84, v85
	s_waitcnt lgkmcnt(1)
	v_mfma_f32_32x32x16_bf16 v[2:17], v[44:47], v[66:69], v[2:17]
	ds_read2_b64 v[78:81], v99 offset0:36 offset1:38
	v_max3_f32 v44, v48, v86, v87
	v_max3_f32 v48, v44, v88, v89
	s_waitcnt lgkmcnt(1)
	v_mfma_f32_32x32x16_bf16 v[18:33], v[74:77], v[70:73], v[18:33]
	ds_read2_b64 v[44:47], v104 offset0:8 offset1:10
	v_max3_f32 v48, v48, v90, v91
	v_max3_f32 v48, v48, v92, v93
	s_waitcnt lgkmcnt(1)
	v_mfma_f32_32x32x16_bf16 v[2:17], v[78:81], v[70:73], v[2:17]
	ds_read2_b64 v[66:69], v99 offset0:40 offset1:42
	v_max3_f32 v48, v48, v94, v95
	v_max3_f32 v48, v48, v96, v97
	s_waitcnt lgkmcnt(1)
	v_mfma_f32_32x32x16_bf16 v[18:33], v[44:47], v[34:37], v[18:33]
	ds_read2_b64 v[70:73], v104 offset0:12 offset1:14
	v_max3_f32 v48, v48, v118, v119
	v_max3_f32 v48, v48, v120, v121
	s_waitcnt lgkmcnt(1)
	v_mfma_f32_32x32x16_bf16 v[2:17], v[66:69], v[34:37], v[2:17]
	ds_read2_b64 v[44:47], v99 offset0:44 offset1:46
	v_max3_f32 v48, v48, v122, v123
	v_max3_f32 v48, v48, v124, v125
	s_waitcnt lgkmcnt(1)
	v_mfma_f32_32x32x16_bf16 v[18:33], v[70:73], v[38:41], v[18:33]
	v_max3_f32 v34, v48, v126, v127
	v_max3_f32 v34, v34, v128, v129
	s_waitcnt lgkmcnt(0)
	v_mfma_f32_32x32x16_bf16 v[2:17], v[44:47], v[38:41], v[2:17]
	v_max3_f32 v34, v34, v130, v131
	v_max3_f32 v208, v34, v132, v133
	s_setprio 0
	v_add_f32_e32 v34, v42, v43
	v_add_f32_e32 v100, v98, v34
	v_add_f32_e64 v34, v222, v208
	v_add_f32_e64 v35, v223, v209
	v_cmp_gt_f32_e32 vcc, v34, v35
	s_cbranch_vccz .LBB0_956
	v_cmp_lt_i32_e32 vcc, v241, v235
	v_max_f32_e32 v35, v208, v208
	v_max_f32_e32 v36, v223, v223
	v_cndmask_b32_e32 v34, v233, v241, vcc
	v_lshlrev_b32_e32 v34, 2, v34
	ds_bpermute_b32 v34, v34, v208
	s_waitcnt lgkmcnt(0)
	v_max_f32_e32 v34, v34, v34
	v_max_f32_e32 v34, v35, v34
	v_add_f32_e32 v34, v222, v34
	v_max_f32_e32 v224, v36, v34
	v_sub_f32_e32 v34, v223, v224
	v_exp_f32_e32 v36, v34
	v_sub_f32_e32 v34, v222, v224
	v_pk_add_f32 v[96:97], v[96:97], v[34:35] op_sel_hi:[1,0]
	v_pk_add_f32 v[94:95], v[94:95], v[34:35] op_sel_hi:[1,0]
	v_pk_add_f32 v[92:93], v[92:93], v[34:35] op_sel_hi:[1,0]
	v_pk_add_f32 v[90:91], v[90:91], v[34:35] op_sel_hi:[1,0]
	v_pk_add_f32 v[88:89], v[88:89], v[34:35] op_sel_hi:[1,0]
	v_pk_add_f32 v[86:87], v[86:87], v[34:35] op_sel_hi:[1,0]
	v_pk_add_f32 v[84:85], v[84:85], v[34:35] op_sel_hi:[1,0]
	v_pk_add_f32 v[82:83], v[82:83], v[34:35] op_sel_hi:[1,0]
	v_pk_add_f32 v[132:133], v[132:133], v[34:35] op_sel_hi:[1,0]
	v_pk_add_f32 v[130:131], v[130:131], v[34:35] op_sel_hi:[1,0]
	v_pk_add_f32 v[128:129], v[128:129], v[34:35] op_sel_hi:[1,0]
	v_pk_add_f32 v[126:127], v[126:127], v[34:35] op_sel_hi:[1,0]
	v_pk_add_f32 v[124:125], v[124:125], v[34:35] op_sel_hi:[1,0]
	v_pk_add_f32 v[122:123], v[122:123], v[34:35] op_sel_hi:[1,0]
	v_pk_add_f32 v[120:121], v[120:121], v[34:35] op_sel_hi:[1,0]
	v_pk_add_f32 v[118:119], v[118:119], v[34:35] op_sel_hi:[1,0]
	v_xor_b32_e32 v34, 0x80000000, v224
	v_pk_mul_f32 v[16:17], v[16:17], v[36:37] op_sel_hi:[1,0]
	v_pk_mul_f32 v[14:15], v[14:15], v[36:37] op_sel_hi:[1,0]
	v_pk_mul_f32 v[12:13], v[12:13], v[36:37] op_sel_hi:[1,0]
	v_pk_mul_f32 v[10:11], v[10:11], v[36:37] op_sel_hi:[1,0]
	v_pk_mul_f32 v[8:9], v[8:9], v[36:37] op_sel_hi:[1,0]
	v_pk_mul_f32 v[6:7], v[6:7], v[36:37] op_sel_hi:[1,0]
	v_pk_mul_f32 v[4:5], v[4:5], v[36:37] op_sel_hi:[1,0]
	v_pk_mul_f32 v[2:3], v[2:3], v[36:37] op_sel_hi:[1,0]
	v_pk_mul_f32 v[32:33], v[32:33], v[36:37] op_sel_hi:[1,0]
	v_pk_mul_f32 v[30:31], v[30:31], v[36:37] op_sel_hi:[1,0]
	v_pk_mul_f32 v[28:29], v[28:29], v[36:37] op_sel_hi:[1,0]
	v_pk_mul_f32 v[26:27], v[26:27], v[36:37] op_sel_hi:[1,0]
	v_pk_mul_f32 v[24:25], v[24:25], v[36:37] op_sel_hi:[1,0]
	v_pk_mul_f32 v[22:23], v[22:23], v[36:37] op_sel_hi:[1,0]
	v_pk_mul_f32 v[20:21], v[20:21], v[36:37] op_sel_hi:[1,0]
	v_pk_mul_f32 v[18:19], v[18:19], v[36:37] op_sel_hi:[1,0]
	v_mul_f32_e32 v100, v100, v36
	v_mov_b32_e32 v225, v224
	v_mov_b32_e32 v35, v34
	v_mov_b32_e32 v36, v34
	v_mov_b32_e32 v37, v34
	v_mov_b32_e32 v38, v34
	v_mov_b32_e32 v39, v34
	v_mov_b32_e32 v40, v34
	v_mov_b32_e32 v41, v34
	v_mov_b32_e32 v42, v34
	v_mov_b32_e32 v43, v34
	v_mov_b32_e32 v44, v34
	v_mov_b32_e32 v45, v34
	v_mov_b32_e32 v46, v34
	v_mov_b32_e32 v47, v34
	v_mov_b32_e32 v48, v34
	v_mov_b32_e32 v49, v34
	v_mov_b32_e32 v50, v34
	v_mov_b32_e32 v51, v34
	v_mov_b32_e32 v52, v34
	v_mov_b32_e32 v53, v34
	v_mov_b32_e32 v54, v34
	v_mov_b32_e32 v55, v34
	v_mov_b32_e32 v56, v34
	v_mov_b32_e32 v57, v34
	v_mov_b32_e32 v58, v34
	v_mov_b32_e32 v59, v34
	v_mov_b32_e32 v60, v34
	v_mov_b32_e32 v61, v34
	v_mov_b32_e32 v62, v34
	v_mov_b32_e32 v63, v34
	v_mov_b32_e32 v64, v34
	v_mov_b32_e32 v65, v34
	v_mov_b32_e32 v222, v224
	v_mov_b32_e32 v223, v224
	s_waitcnt vmcnt(7)
	ds_write_b128 v1, v[182:185]
	s_and_saveexec_b64 s[4:5], s[2:3]

.LBB0_942:
	s_or_b64 exec, exec, s[6:7]
	s_add_i32 s4, s10, 1
	s_cmp_lg_u32 s10, 4
	s_cselect_b32 s10, s4, 0
	s_lshl_b32 s84, s14, 7
	v_lshl_add_u64 v[66:67], v[220:221], 0, s[84:85]
	global_load_dwordx4 v[194:197], v[66:67], off
	ds_read_b128 v[102:105], v249 offset:26624
	ds_read_b128 v[106:109], v249 offset:26656
	s_mul_i32 s4, s10, 0x2200
	v_add_u32_e32 v101, s4, v248
	s_waitcnt lgkmcnt(1)
	v_mfma_f32_32x32x16_bf16 v[66:81], v[102:105], v[134:137], v[34:49]
	ds_read_b128 v[110:113], v249 offset:26688
	v_exp_f32_e32 v98, v82
	v_exp_f32_e32 v99, v83
	v_exp_f32_e32 v84, v84
	v_exp_f32_e32 v85, v85
	v_cvt_pk_bf16_f32 v82, v98, v99
	v_cvt_pk_bf16_f32 v83, v84, v85
	v_pk_add_f32 v[98:99], v[84:85], v[98:99]
	s_waitcnt lgkmcnt(1)
	v_mfma_f32_32x32x16_bf16 v[66:81], v[106:109], v[138:141], v[66:81]
	v_exp_f32_e32 v86, v86
	v_exp_f32_e32 v87, v87
	ds_read_b128 v[102:105], v249 offset:26720
	v_exp_f32_e32 v88, v88
	v_exp_f32_e32 v89, v89
	v_cvt_pk_bf16_f32 v84, v86, v87
	v_pk_add_f32 v[86:87], v[86:87], v[98:99]
	v_cvt_pk_bf16_f32 v85, v88, v89
	v_pk_add_f32 v[98:99], v[88:89], v[86:87]
	s_waitcnt lgkmcnt(1)
	v_mfma_f32_32x32x16_bf16 v[66:81], v[110:113], v[142:145], v[66:81]
	ds_read_b128 v[106:109], v249 offset:26752
	v_exp_f32_e32 v88, v90
	v_exp_f32_e32 v89, v91
	v_exp_f32_e32 v90, v92
	v_exp_f32_e32 v91, v93
	v_cvt_pk_bf16_f32 v86, v88, v89
	v_pk_add_f32 v[88:89], v[88:89], v[98:99]
	v_cvt_pk_bf16_f32 v87, v90, v91
	v_pk_add_f32 v[92:93], v[90:91], v[88:89]
	s_waitcnt lgkmcnt(1)
	v_mfma_f32_32x32x16_bf16 v[66:81], v[102:105], v[146:149], v[66:81]
	v_exp_f32_e32 v90, v94
	v_exp_f32_e32 v91, v95
	ds_read_b128 v[110:113], v249 offset:26784
	v_cvt_pk_bf16_f32 v88, v90, v91
	v_pk_add_f32 v[90:91], v[90:91], v[92:93]
	v_exp_f32_e32 v92, v96
	v_exp_f32_e32 v93, v97
	s_nop 0
	v_pk_add_f32 v[90:91], v[92:93], v[90:91]
	v_cvt_pk_bf16_f32 v89, v92, v93
	s_waitcnt lgkmcnt(1)
	v_mfma_f32_32x32x16_bf16 v[66:81], v[106:109], v[150:153], v[66:81]
	v_exp_f32_e32 v92, v118
	v_exp_f32_e32 v93, v119
	ds_read_b128 v[94:97], v249 offset:33280
	v_pk_add_f32 v[98:99], v[92:93], v[90:91]
	v_cvt_pk_bf16_f32 v90, v92, v93
	s_waitcnt lgkmcnt(1)
	v_mfma_f32_32x32x16_bf16 v[66:81], v[110:113], v[154:157], v[66:81]
	v_exp_f32_e32 v92, v120
	v_exp_f32_e32 v93, v121
	ds_read_b128 v[102:105], v249 offset:33312
	v_pk_add_f32 v[98:99], v[92:93], v[98:99]
	v_cvt_pk_bf16_f32 v91, v92, v93
	v_exp_f32_e32 v92, v122
	v_exp_f32_e32 v93, v123
	s_waitcnt lgkmcnt(1)
	v_mfma_f32_32x32x16_bf16 v[108:123], v[94:97], v[134:137], v[34:49]
	ds_read_b128 v[236:239], v249 offset:33344
	v_add_f32_e64 v106, v92, v98
	v_add_f32_e64 v107, v93, v99
	v_cvt_pk_bf16_f32 v92, v92, v93
	s_waitcnt lgkmcnt(1)
	v_mfma_f32_32x32x16_bf16 v[108:123], v[102:105], v[138:141], v[108:123]
	v_exp_f32_e32 v94, v124
	v_exp_f32_e32 v95, v125
	ds_read_b128 v[96:99], v249 offset:33376
	v_pk_add_f32 v[106:107], v[94:95], v[106:107]
	v_cvt_pk_bf16_f32 v93, v94, v95
	s_waitcnt lgkmcnt(1)
	v_mfma_f32_32x32x16_bf16 v[108:123], v[236:239], v[142:145], v[108:123]
	v_exp_f32_e32 v94, v126
	v_exp_f32_e32 v95, v127
	ds_read_b128 v[102:105], v249 offset:33408
	v_pk_add_f32 v[106:107], v[94:95], v[106:107]
	v_cvt_pk_bf16_f32 v94, v94, v95
	s_waitcnt lgkmcnt(1)
	v_mfma_f32_32x32x16_bf16 v[108:123], v[96:99], v[146:149], v[108:123]
	v_exp_f32_e32 v96, v128
	v_exp_f32_e32 v97, v129
	ds_read_b128 v[124:127], v249 offset:33440
	v_pk_add_f32 v[98:99], v[96:97], v[106:107]
	v_cvt_pk_bf16_f32 v95, v96, v97
	s_waitcnt lgkmcnt(1)
	v_mfma_f32_32x32x16_bf16 v[108:123], v[102:105], v[150:153], v[108:123]
	v_add_u32_e32 v208, 0xd000, v101
	v_exp_f32_e32 v96, v130
	v_exp_f32_e32 v97, v131
	ds_read2_b64 v[236:239], v208 offset1:2
	v_pk_add_f32 v[98:99], v[96:97], v[98:99]
	v_cvt_pk_bf16_f32 v96, v96, v97
	s_waitcnt lgkmcnt(1)
	v_mfma_f32_32x32x16_bf16 v[108:123], v[124:127], v[154:157], v[108:123]
	v_add_u32_e32 v101, 0xe000, v101
	v_exp_f32_e32 v106, v132
	v_exp_f32_e32 v107, v133
	ds_read2_b64 v[102:105], v101 offset0:32 offset1:34
	v_pk_add_f32 v[98:99], v[106:107], v[98:99]
	v_cvt_pk_bf16_f32 v97, v106, v107
	s_setprio 1
	s_waitcnt lgkmcnt(1)
	v_mfma_f32_32x32x16_bf16 v[18:33], v[236:239], v[82:85], v[18:33]
	ds_read2_b64 v[124:127], v208 offset0:4 offset1:6
	v_max3_f32 v106, v231, v66, v67
	v_max3_f32 v106, v106, v68, v69
	s_waitcnt lgkmcnt(1)
	v_mfma_f32_32x32x16_bf16 v[2:17], v[102:105], v[82:85], v[2:17]
	ds_read2_b64 v[128:131], v101 offset0:36 offset1:38
	v_max3_f32 v82, v106, v70, v71
	v_max3_f32 v102, v82, v72, v73
	s_waitcnt lgkmcnt(1)
	v_mfma_f32_32x32x16_bf16 v[18:33], v[124:127], v[86:89], v[18:33]
	ds_read2_b64 v[82:85], v208 offset0:8 offset1:10
	v_max3_f32 v102, v102, v74, v75
	v_max3_f32 v106, v102, v76, v77
	s_waitcnt lgkmcnt(1)
	v_mfma_f32_32x32x16_bf16 v[2:17], v[128:131], v[86:89], v[2:17]
	ds_read2_b64 v[102:105], v101 offset0:40 offset1:42
	v_max3_f32 v86, v106, v78, v79
	v_max3_f32 v106, v86, v80, v81
	s_waitcnt lgkmcnt(1)
	v_mfma_f32_32x32x16_bf16 v[18:33], v[82:85], v[90:93], v[18:33]
	ds_read2_b64 v[86:89], v208 offset0:12 offset1:14
	v_max3_f32 v106, v106, v108, v109
	v_max3_f32 v106, v106, v110, v111
	s_waitcnt lgkmcnt(1)
	v_mfma_f32_32x32x16_bf16 v[2:17], v[102:105], v[90:93], v[2:17]
	ds_read2_b64 v[82:85], v101 offset0:44 offset1:46
	v_max3_f32 v101, v106, v112, v113
	v_max3_f32 v101, v101, v114, v115
	s_waitcnt lgkmcnt(1)
	v_mfma_f32_32x32x16_bf16 v[18:33], v[86:89], v[94:97], v[18:33]
	v_max3_f32 v86, v101, v116, v117
	v_max3_f32 v86, v86, v118, v119
	s_waitcnt lgkmcnt(0)
	v_mfma_f32_32x32x16_bf16 v[2:17], v[82:85], v[94:97], v[2:17]
	v_max3_f32 v82, v86, v120, v121
	v_max3_f32 v208, v82, v122, v123
	s_setprio 0
	v_add_f32_e32 v82, v98, v99
	v_add_f32_e32 v124, v100, v82
	v_add_f32_e64 v82, v224, v208
	v_add_f32_e64 v83, v225, v209
	v_cmp_gt_f32_e32 vcc, v82, v83
	s_cbranch_vccz .LBB0_944
	v_cmp_lt_i32_e32 vcc, v241, v235
	v_max_f32_e32 v35, v208, v208
	v_max_f32_e32 v36, v223, v223
	v_cndmask_b32_e32 v34, v233, v241, vcc
	v_lshlrev_b32_e32 v34, 2, v34
	ds_bpermute_b32 v34, v34, v208
	s_waitcnt lgkmcnt(0)
	v_max_f32_e32 v34, v34, v34
	v_max_f32_e32 v34, v35, v34
	v_add_f32_e32 v34, v222, v34
	v_max_f32_e32 v224, v36, v34
	v_sub_f32_e32 v34, v223, v224
	v_exp_f32_e32 v36, v34
	v_sub_f32_e32 v34, v222, v224
	v_pk_add_f32 v[80:81], v[80:81], v[34:35] op_sel_hi:[1,0]
	v_pk_add_f32 v[78:79], v[78:79], v[34:35] op_sel_hi:[1,0]
	v_pk_add_f32 v[76:77], v[76:77], v[34:35] op_sel_hi:[1,0]
	v_pk_add_f32 v[74:75], v[74:75], v[34:35] op_sel_hi:[1,0]
	v_pk_add_f32 v[72:73], v[72:73], v[34:35] op_sel_hi:[1,0]
	v_pk_add_f32 v[70:71], v[70:71], v[34:35] op_sel_hi:[1,0]
	v_pk_add_f32 v[68:69], v[68:69], v[34:35] op_sel_hi:[1,0]
	v_pk_add_f32 v[66:67], v[66:67], v[34:35] op_sel_hi:[1,0]
	v_pk_add_f32 v[122:123], v[122:123], v[34:35] op_sel_hi:[1,0]
	v_pk_add_f32 v[120:121], v[120:121], v[34:35] op_sel_hi:[1,0]
	v_pk_add_f32 v[118:119], v[118:119], v[34:35] op_sel_hi:[1,0]
	v_pk_add_f32 v[116:117], v[116:117], v[34:35] op_sel_hi:[1,0]
	v_pk_add_f32 v[114:115], v[114:115], v[34:35] op_sel_hi:[1,0]
	v_pk_add_f32 v[112:113], v[112:113], v[34:35] op_sel_hi:[1,0]
	v_pk_add_f32 v[110:111], v[110:111], v[34:35] op_sel_hi:[1,0]
	v_pk_add_f32 v[108:109], v[108:109], v[34:35] op_sel_hi:[1,0]
	v_xor_b32_e32 v34, 0x80000000, v224
	v_pk_mul_f32 v[16:17], v[16:17], v[36:37] op_sel_hi:[1,0]
	v_pk_mul_f32 v[14:15], v[14:15], v[36:37] op_sel_hi:[1,0]
	v_pk_mul_f32 v[12:13], v[12:13], v[36:37] op_sel_hi:[1,0]
	v_pk_mul_f32 v[10:11], v[10:11], v[36:37] op_sel_hi:[1,0]
	v_pk_mul_f32 v[8:9], v[8:9], v[36:37] op_sel_hi:[1,0]
	v_pk_mul_f32 v[6:7], v[6:7], v[36:37] op_sel_hi:[1,0]
	v_pk_mul_f32 v[4:5], v[4:5], v[36:37] op_sel_hi:[1,0]
	v_pk_mul_f32 v[2:3], v[2:3], v[36:37] op_sel_hi:[1,0]
	v_pk_mul_f32 v[32:33], v[32:33], v[36:37] op_sel_hi:[1,0]
	v_pk_mul_f32 v[30:31], v[30:31], v[36:37] op_sel_hi:[1,0]
	v_pk_mul_f32 v[28:29], v[28:29], v[36:37] op_sel_hi:[1,0]
	v_pk_mul_f32 v[26:27], v[26:27], v[36:37] op_sel_hi:[1,0]
	v_pk_mul_f32 v[24:25], v[24:25], v[36:37] op_sel_hi:[1,0]
	v_pk_mul_f32 v[22:23], v[22:23], v[36:37] op_sel_hi:[1,0]
	v_pk_mul_f32 v[20:21], v[20:21], v[36:37] op_sel_hi:[1,0]
	v_pk_mul_f32 v[18:19], v[18:19], v[36:37] op_sel_hi:[1,0]
	v_mul_f32_e32 v124, v124, v36
	v_mov_b32_e32 v225, v224
	v_mov_b32_e32 v35, v34
	v_mov_b32_e32 v36, v34
	v_mov_b32_e32 v37, v34
	v_mov_b32_e32 v38, v34
	v_mov_b32_e32 v39, v34
	v_mov_b32_e32 v40, v34
	v_mov_b32_e32 v41, v34
	v_mov_b32_e32 v42, v34
	v_mov_b32_e32 v43, v34
	v_mov_b32_e32 v44, v34
	v_mov_b32_e32 v45, v34
	v_mov_b32_e32 v46, v34
	v_mov_b32_e32 v47, v34
	v_mov_b32_e32 v48, v34
	v_mov_b32_e32 v49, v34
	v_mov_b32_e32 v50, v34
	v_mov_b32_e32 v51, v34
	v_mov_b32_e32 v52, v34
	v_mov_b32_e32 v53, v34
	v_mov_b32_e32 v54, v34
	v_mov_b32_e32 v55, v34
	v_mov_b32_e32 v56, v34
	v_mov_b32_e32 v57, v34
	v_mov_b32_e32 v58, v34
	v_mov_b32_e32 v59, v34
	v_mov_b32_e32 v60, v34
	v_mov_b32_e32 v61, v34
	v_mov_b32_e32 v62, v34
	v_mov_b32_e32 v63, v34
	v_mov_b32_e32 v64, v34
	v_mov_b32_e32 v65, v34
	v_mov_b32_e32 v222, v224
	v_mov_b32_e32 v223, v224

.LBB0_948:
	s_or_b64 exec, exec, s[6:7]
	s_add_i32 s4, s10, 1
	s_cmp_lg_u32 s10, 4
	s_cselect_b32 s10, s4, 0
	s_lshl_b32 s84, s14, 7
	v_lshl_add_u64 v[82:83], v[220:221], 0, s[84:85]
	global_load_dwordx4 v[198:201], v[82:83], off
	ds_read_b128 v[98:101], v249 offset:39936
	ds_read_b128 v[102:105], v249 offset:39968
	s_mul_i32 s4, s10, 0x2200
	v_add_u32_e32 v125, s4, v248
	s_waitcnt lgkmcnt(1)
	v_mfma_f32_32x32x16_bf16 v[82:97], v[98:101], v[134:137], v[34:49]
	v_exp_f32_e32 v98, v66
	v_exp_f32_e32 v99, v67
	v_exp_f32_e32 v68, v68
	v_exp_f32_e32 v69, v69
	ds_read_b128 v[126:129], v249 offset:40000
	v_cvt_pk_bf16_f32 v66, v98, v99
	v_cvt_pk_bf16_f32 v67, v68, v69
	v_pk_add_f32 v[106:107], v[68:69], v[98:99]
	s_waitcnt lgkmcnt(1)
	v_mfma_f32_32x32x16_bf16 v[82:97], v[102:105], v[138:141], v[82:97]
	v_exp_f32_e32 v70, v70
	v_exp_f32_e32 v71, v71
	ds_read_b128 v[98:101], v249 offset:40032
	v_exp_f32_e32 v72, v72
	v_exp_f32_e32 v73, v73
	v_cvt_pk_bf16_f32 v68, v70, v71
	v_pk_add_f32 v[70:71], v[70:71], v[106:107]
	v_cvt_pk_bf16_f32 v69, v72, v73
	v_pk_add_f32 v[106:107], v[72:73], v[70:71]
	s_waitcnt lgkmcnt(1)
	v_mfma_f32_32x32x16_bf16 v[82:97], v[126:129], v[142:145], v[82:97]
	ds_read_b128 v[102:105], v249 offset:40064
	v_exp_f32_e32 v72, v74
	v_exp_f32_e32 v73, v75
	v_exp_f32_e32 v74, v76
	v_exp_f32_e32 v75, v77
	v_cvt_pk_bf16_f32 v70, v72, v73
	v_pk_add_f32 v[72:73], v[72:73], v[106:107]
	v_cvt_pk_bf16_f32 v71, v74, v75
	v_pk_add_f32 v[76:77], v[74:75], v[72:73]
	s_waitcnt lgkmcnt(1)
	v_mfma_f32_32x32x16_bf16 v[82:97], v[98:101], v[146:149], v[82:97]
	v_exp_f32_e32 v74, v78
	v_exp_f32_e32 v75, v79
	ds_read_b128 v[126:129], v249 offset:40096
	v_cvt_pk_bf16_f32 v72, v74, v75
	v_pk_add_f32 v[74:75], v[74:75], v[76:77]
	v_exp_f32_e32 v76, v80
	v_exp_f32_e32 v77, v81
	s_nop 0
	v_pk_add_f32 v[74:75], v[76:77], v[74:75]
	v_cvt_pk_bf16_f32 v73, v76, v77
	s_waitcnt lgkmcnt(1)
	v_mfma_f32_32x32x16_bf16 v[82:97], v[102:105], v[150:153], v[82:97]
	v_exp_f32_e32 v76, v108
	v_exp_f32_e32 v77, v109
	ds_read_b128 v[78:81], v249 offset:46592
	v_pk_add_f32 v[98:99], v[76:77], v[74:75]
	v_cvt_pk_bf16_f32 v74, v76, v77
	s_waitcnt lgkmcnt(1)
	v_mfma_f32_32x32x16_bf16 v[82:97], v[126:129], v[154:157], v[82:97]
	v_exp_f32_e32 v76, v110
	v_exp_f32_e32 v77, v111
	ds_read_b128 v[130:133], v249 offset:46624
	v_pk_add_f32 v[98:99], v[76:77], v[98:99]
	v_cvt_pk_bf16_f32 v75, v76, v77
	v_exp_f32_e32 v76, v112
	v_exp_f32_e32 v77, v113
	ds_read_b128 v[126:129], v249 offset:46656
	v_pk_add_f32 v[250:251], v[76:77], v[98:99]
	s_waitcnt lgkmcnt(2)
	v_mfma_f32_32x32x16_bf16 v[98:113], v[78:81], v[134:137], v[34:49]
	v_cvt_pk_bf16_f32 v76, v76, v77
	s_waitcnt lgkmcnt(1)
	v_mfma_f32_32x32x16_bf16 v[98:113], v[130:133], v[138:141], v[98:113]
	v_exp_f32_e32 v78, v114
	v_exp_f32_e32 v79, v115
	ds_read_b128 v[236:239], v249 offset:46688
	v_pk_add_f32 v[80:81], v[78:79], v[250:251]
	v_cvt_pk_bf16_f32 v77, v78, v79
	s_waitcnt lgkmcnt(1)
	v_mfma_f32_32x32x16_bf16 v[98:113], v[126:129], v[142:145], v[98:113]
	v_exp_f32_e32 v78, v116
	v_exp_f32_e32 v79, v117
	ds_read_b128 v[130:133], v249 offset:46720
	v_pk_add_f32 v[80:81], v[78:79], v[80:81]
	v_cvt_pk_bf16_f32 v78, v78, v79
	s_waitcnt lgkmcnt(1)
	v_mfma_f32_32x32x16_bf16 v[98:113], v[236:239], v[146:149], v[98:113]
	v_exp_f32_e32 v114, v118
	v_exp_f32_e32 v115, v119
	ds_read_b128 v[126:129], v249 offset:46752
	v_pk_add_f32 v[80:81], v[114:115], v[80:81]
	v_cvt_pk_bf16_f32 v79, v114, v115
	s_waitcnt lgkmcnt(1)
	v_mfma_f32_32x32x16_bf16 v[98:113], v[130:133], v[150:153], v[98:113]
	v_add_u32_e32 v208, 0xd000, v125
	v_exp_f32_e32 v114, v120
	v_exp_f32_e32 v115, v121
	ds_read2_b64 v[116:119], v208 offset1:2
	v_pk_add_f32 v[130:131], v[114:115], v[80:81]
	v_cvt_pk_bf16_f32 v80, v114, v115
	s_waitcnt lgkmcnt(1)
	v_mfma_f32_32x32x16_bf16 v[98:113], v[126:129], v[154:157], v[98:113]
	v_exp_f32_e32 v132, v122
	v_exp_f32_e32 v133, v123
	v_add_u32_e32 v125, 0xe000, v125
	ds_read2_b64 v[120:123], v125 offset0:32 offset1:34
	v_pk_add_f32 v[114:115], v[132:133], v[130:131]
	v_cvt_pk_bf16_f32 v81, v132, v133
	s_setprio 1
	s_waitcnt lgkmcnt(1)
	v_mfma_f32_32x32x16_bf16 v[18:33], v[116:119], v[66:69], v[18:33]
	ds_read2_b64 v[126:129], v208 offset0:4 offset1:6
	v_max3_f32 v116, v231, v82, v83
	v_max3_f32 v130, v116, v84, v85
	s_waitcnt lgkmcnt(1)
	v_mfma_f32_32x32x16_bf16 v[2:17], v[120:123], v[66:69], v[2:17]
	ds_read2_b64 v[116:119], v125 offset0:36 offset1:38
	v_max3_f32 v66, v130, v86, v87
	v_max3_f32 v120, v66, v88, v89
	s_waitcnt lgkmcnt(1)
	v_mfma_f32_32x32x16_bf16 v[18:33], v[126:129], v[70:73], v[18:33]
	ds_read2_b64 v[66:69], v208 offset0:8 offset1:10
	v_max3_f32 v120, v120, v90, v91
	v_max3_f32 v126, v120, v92, v93
	s_waitcnt lgkmcnt(1)
	v_mfma_f32_32x32x16_bf16 v[2:17], v[116:119], v[70:73], v[2:17]
	ds_read2_b64 v[120:123], v125 offset0:40 offset1:42
	v_max3_f32 v70, v126, v94, v95
	v_max3_f32 v116, v70, v96, v97
	s_waitcnt lgkmcnt(1)
	v_mfma_f32_32x32x16_bf16 v[18:33], v[66:69], v[74:77], v[18:33]
	ds_read2_b64 v[70:73], v208 offset0:12 offset1:14
	v_max3_f32 v116, v116, v98, v99
	v_max3_f32 v116, v116, v100, v101
	s_waitcnt lgkmcnt(1)
	v_mfma_f32_32x32x16_bf16 v[2:17], v[120:123], v[74:77], v[2:17]
	ds_read2_b64 v[66:69], v125 offset0:44 offset1:46
	v_max3_f32 v116, v116, v102, v103
	v_max3_f32 v116, v116, v104, v105
	s_waitcnt lgkmcnt(1)
	v_mfma_f32_32x32x16_bf16 v[18:33], v[70:73], v[78:81], v[18:33]
	v_max3_f32 v70, v116, v106, v107
	v_max3_f32 v70, v70, v108, v109
	s_waitcnt lgkmcnt(0)
	v_mfma_f32_32x32x16_bf16 v[2:17], v[66:69], v[78:81], v[2:17]
	v_max3_f32 v66, v70, v110, v111
	v_max3_f32 v208, v66, v112, v113
	s_setprio 0
	v_add_f32_e32 v66, v114, v115
	v_add_f32_e32 v114, v124, v66
	v_add_f32_e64 v66, v224, v208
	v_add_f32_e64 v67, v225, v209
	v_cmp_gt_f32_e32 vcc, v66, v67
	s_cbranch_vccz .LBB0_950
	v_cmp_lt_i32_e32 vcc, v241, v235
	v_max_f32_e32 v35, v208, v208
	v_max_f32_e32 v36, v223, v223
	v_cndmask_b32_e32 v34, v233, v241, vcc
	v_lshlrev_b32_e32 v34, 2, v34
	ds_bpermute_b32 v34, v34, v208
	s_waitcnt lgkmcnt(0)
	v_max_f32_e32 v34, v34, v34
	v_max_f32_e32 v34, v35, v34
	v_add_f32_e32 v34, v222, v34
	v_max_f32_e32 v224, v36, v34
	v_sub_f32_e32 v34, v223, v224
	v_exp_f32_e32 v36, v34
	v_sub_f32_e32 v34, v222, v224
	v_pk_add_f32 v[96:97], v[96:97], v[34:35] op_sel_hi:[1,0]
	v_pk_add_f32 v[94:95], v[94:95], v[34:35] op_sel_hi:[1,0]
	v_pk_add_f32 v[92:93], v[92:93], v[34:35] op_sel_hi:[1,0]
	v_pk_add_f32 v[90:91], v[90:91], v[34:35] op_sel_hi:[1,0]
	v_pk_add_f32 v[88:89], v[88:89], v[34:35] op_sel_hi:[1,0]
	v_pk_add_f32 v[86:87], v[86:87], v[34:35] op_sel_hi:[1,0]
	v_pk_add_f32 v[84:85], v[84:85], v[34:35] op_sel_hi:[1,0]
	v_pk_add_f32 v[82:83], v[82:83], v[34:35] op_sel_hi:[1,0]
	v_pk_add_f32 v[112:113], v[112:113], v[34:35] op_sel_hi:[1,0]
	v_pk_add_f32 v[110:111], v[110:111], v[34:35] op_sel_hi:[1,0]
	v_pk_add_f32 v[108:109], v[108:109], v[34:35] op_sel_hi:[1,0]
	v_pk_add_f32 v[106:107], v[106:107], v[34:35] op_sel_hi:[1,0]
	v_pk_add_f32 v[104:105], v[104:105], v[34:35] op_sel_hi:[1,0]
	v_pk_add_f32 v[102:103], v[102:103], v[34:35] op_sel_hi:[1,0]
	v_pk_add_f32 v[100:101], v[100:101], v[34:35] op_sel_hi:[1,0]
	v_pk_add_f32 v[98:99], v[98:99], v[34:35] op_sel_hi:[1,0]
	v_xor_b32_e32 v34, 0x80000000, v224
	v_pk_mul_f32 v[16:17], v[16:17], v[36:37] op_sel_hi:[1,0]
	v_pk_mul_f32 v[14:15], v[14:15], v[36:37] op_sel_hi:[1,0]
	v_pk_mul_f32 v[12:13], v[12:13], v[36:37] op_sel_hi:[1,0]
	v_pk_mul_f32 v[10:11], v[10:11], v[36:37] op_sel_hi:[1,0]
	v_pk_mul_f32 v[8:9], v[8:9], v[36:37] op_sel_hi:[1,0]
	v_pk_mul_f32 v[6:7], v[6:7], v[36:37] op_sel_hi:[1,0]
	v_pk_mul_f32 v[4:5], v[4:5], v[36:37] op_sel_hi:[1,0]
	v_pk_mul_f32 v[2:3], v[2:3], v[36:37] op_sel_hi:[1,0]
	v_pk_mul_f32 v[32:33], v[32:33], v[36:37] op_sel_hi:[1,0]
	v_pk_mul_f32 v[30:31], v[30:31], v[36:37] op_sel_hi:[1,0]
	v_pk_mul_f32 v[28:29], v[28:29], v[36:37] op_sel_hi:[1,0]
	v_pk_mul_f32 v[26:27], v[26:27], v[36:37] op_sel_hi:[1,0]
	v_pk_mul_f32 v[24:25], v[24:25], v[36:37] op_sel_hi:[1,0]
	v_pk_mul_f32 v[22:23], v[22:23], v[36:37] op_sel_hi:[1,0]
	v_pk_mul_f32 v[20:21], v[20:21], v[36:37] op_sel_hi:[1,0]
	v_pk_mul_f32 v[18:19], v[18:19], v[36:37] op_sel_hi:[1,0]
	v_mul_f32_e32 v114, v114, v36
	v_mov_b32_e32 v225, v224
	v_mov_b32_e32 v35, v34
	v_mov_b32_e32 v36, v34
	v_mov_b32_e32 v37, v34
	v_mov_b32_e32 v38, v34
	v_mov_b32_e32 v39, v34
	v_mov_b32_e32 v40, v34
	v_mov_b32_e32 v41, v34
	v_mov_b32_e32 v42, v34
	v_mov_b32_e32 v43, v34
	v_mov_b32_e32 v44, v34
	v_mov_b32_e32 v45, v34
	v_mov_b32_e32 v46, v34
	v_mov_b32_e32 v47, v34
	v_mov_b32_e32 v48, v34
	v_mov_b32_e32 v49, v34
	v_mov_b32_e32 v50, v34
	v_mov_b32_e32 v51, v34
	v_mov_b32_e32 v52, v34
	v_mov_b32_e32 v53, v34
	v_mov_b32_e32 v54, v34
	v_mov_b32_e32 v55, v34
	v_mov_b32_e32 v56, v34
	v_mov_b32_e32 v57, v34
	v_mov_b32_e32 v58, v34
	v_mov_b32_e32 v59, v34
	v_mov_b32_e32 v60, v34
	v_mov_b32_e32 v61, v34
	v_mov_b32_e32 v62, v34
	v_mov_b32_e32 v63, v34
	v_mov_b32_e32 v64, v34
	v_mov_b32_e32 v65, v34
	v_mov_b32_e32 v222, v224
	v_mov_b32_e32 v223, v224

.LBB0_954:
	s_or_b64 exec, exec, s[6:7]
	s_add_i32 s4, s10, 1
	s_cmp_lg_u32 s10, 4
	s_cselect_b32 s4, s4, 0
	s_lshl_b32 s84, s14, 7
	v_lshl_add_u64 v[66:67], v[220:221], 0, s[84:85]
	global_load_dwordx4 v[202:205], v[66:67], off
	ds_read_b128 v[116:119], v249
	ds_read_b128 v[120:123], v249 offset:32
	s_mul_i32 s5, s4, 0x2200
	v_add_u32_e32 v115, s5, v248
	s_waitcnt lgkmcnt(1)
	v_mfma_f32_32x32x16_bf16 v[66:81], v[116:119], v[134:137], v[34:49]
	v_exp_f32_e32 v116, v82
	v_exp_f32_e32 v117, v83
	ds_read_b128 v[124:127], v249 offset:64
	v_exp_f32_e32 v84, v84
	v_exp_f32_e32 v85, v85
	v_cvt_pk_bf16_f32 v82, v116, v117
	v_cvt_pk_bf16_f32 v83, v84, v85
	v_pk_add_f32 v[128:129], v[84:85], v[116:117]
	s_waitcnt lgkmcnt(1)
	v_mfma_f32_32x32x16_bf16 v[66:81], v[120:123], v[138:141], v[66:81]
	v_exp_f32_e32 v86, v86
	v_exp_f32_e32 v87, v87
	ds_read_b128 v[116:119], v249 offset:96
	v_exp_f32_e32 v88, v88
	v_exp_f32_e32 v89, v89
	v_cvt_pk_bf16_f32 v84, v86, v87
	v_pk_add_f32 v[86:87], v[86:87], v[128:129]
	v_cvt_pk_bf16_f32 v85, v88, v89
	v_pk_add_f32 v[128:129], v[88:89], v[86:87]
	s_waitcnt lgkmcnt(1)
	v_mfma_f32_32x32x16_bf16 v[66:81], v[124:127], v[142:145], v[66:81]
	v_exp_f32_e32 v88, v90
	v_exp_f32_e32 v89, v91
	ds_read_b128 v[120:123], v249 offset:128
	v_exp_f32_e32 v90, v92
	v_exp_f32_e32 v91, v93
	v_cvt_pk_bf16_f32 v86, v88, v89
	v_pk_add_f32 v[88:89], v[88:89], v[128:129]
	v_cvt_pk_bf16_f32 v87, v90, v91
	v_pk_add_f32 v[92:93], v[90:91], v[88:89]
	s_waitcnt lgkmcnt(1)
	v_mfma_f32_32x32x16_bf16 v[66:81], v[116:119], v[146:149], v[66:81]
	v_exp_f32_e32 v90, v94
	v_exp_f32_e32 v91, v95
	ds_read_b128 v[124:127], v249 offset:160
	v_cvt_pk_bf16_f32 v88, v90, v91
	v_pk_add_f32 v[90:91], v[90:91], v[92:93]
	v_exp_f32_e32 v92, v96
	v_exp_f32_e32 v93, v97
	s_nop 0
	v_pk_add_f32 v[90:91], v[92:93], v[90:91]
	v_cvt_pk_bf16_f32 v89, v92, v93
	s_waitcnt lgkmcnt(1)
	v_mfma_f32_32x32x16_bf16 v[66:81], v[120:123], v[150:153], v[66:81]
	v_exp_f32_e32 v96, v98
	v_exp_f32_e32 v97, v99
	ds_read_b128 v[92:95], v249 offset:6656
	v_pk_add_f32 v[116:117], v[96:97], v[90:91]
	v_cvt_pk_bf16_f32 v90, v96, v97
	s_waitcnt lgkmcnt(1)
	v_mfma_f32_32x32x16_bf16 v[66:81], v[124:127], v[154:157], v[66:81]
	v_exp_f32_e32 v100, v100
	v_exp_f32_e32 v101, v101
	ds_read_b128 v[96:99], v249 offset:6688
	v_pk_add_f32 v[120:121], v[100:101], v[116:117]
	v_cvt_pk_bf16_f32 v91, v100, v101
	s_waitcnt lgkmcnt(1)
	v_mfma_f32_32x32x16_bf16 v[34:49], v[92:95], v[134:137], v[34:49]
	v_exp_f32_e32 v92, v102
	v_exp_f32_e32 v93, v103
	ds_read_b128 v[116:119], v249 offset:6720
	v_pk_add_f32 v[94:95], v[92:93], v[120:121]
	v_cvt_pk_bf16_f32 v92, v92, v93
	s_waitcnt lgkmcnt(1)
	v_mfma_f32_32x32x16_bf16 v[34:49], v[96:99], v[138:141], v[34:49]
	v_exp_f32_e32 v96, v104
	v_exp_f32_e32 v97, v105
	ds_read_b128 v[100:103], v249 offset:6752
	v_pk_add_f32 v[94:95], v[96:97], v[94:95]
	v_cvt_pk_bf16_f32 v93, v96, v97
	s_waitcnt lgkmcnt(1)
	v_mfma_f32_32x32x16_bf16 v[34:49], v[116:119], v[142:145], v[34:49]
	v_exp_f32_e32 v104, v106
	v_exp_f32_e32 v105, v107
	ds_read_b128 v[96:99], v249 offset:6784
	v_pk_add_f32 v[116:117], v[104:105], v[94:95]
	v_cvt_pk_bf16_f32 v94, v104, v105
	s_waitcnt lgkmcnt(1)
	v_mfma_f32_32x32x16_bf16 v[34:49], v[100:103], v[146:149], v[34:49]
	v_exp_f32_e32 v100, v108
	v_exp_f32_e32 v101, v109
	ds_read_b128 v[104:107], v249 offset:6816
	v_pk_add_f32 v[108:109], v[100:101], v[116:117]
	v_cvt_pk_bf16_f32 v95, v100, v101
	s_waitcnt lgkmcnt(1)
	v_mfma_f32_32x32x16_bf16 v[34:49], v[96:99], v[150:153], v[34:49]
	v_add_u32_e32 v116, 0xd000, v115
	v_exp_f32_e32 v96, v110
	v_exp_f32_e32 v97, v111
	ds_read2_b64 v[100:103], v116 offset1:2
	v_pk_add_f32 v[98:99], v[96:97], v[108:109]
	v_cvt_pk_bf16_f32 v96, v96, v97
	s_waitcnt lgkmcnt(1)
	v_mfma_f32_32x32x16_bf16 v[34:49], v[104:107], v[154:157], v[34:49]
	v_exp_f32_e32 v112, v112
	v_exp_f32_e32 v113, v113
	v_add_u32_e32 v115, 0xe000, v115
	ds_read2_b64 v[108:111], v115 offset0:32 offset1:34
	v_pk_add_f32 v[98:99], v[112:113], v[98:99]
	v_cvt_pk_bf16_f32 v97, v112, v113
	s_setprio 1
	s_waitcnt lgkmcnt(1)
	v_mfma_f32_32x32x16_bf16 v[18:33], v[100:103], v[82:85], v[18:33]
	ds_read2_b64 v[104:107], v116 offset0:4 offset1:6
	v_max3_f32 v100, v231, v66, v67
	v_max3_f32 v112, v100, v68, v69
	s_waitcnt lgkmcnt(1)
	v_mfma_f32_32x32x16_bf16 v[2:17], v[108:111], v[82:85], v[2:17]
	ds_read2_b64 v[100:103], v115 offset0:36 offset1:38
	v_max3_f32 v82, v112, v70, v71
	v_max3_f32 v108, v82, v72, v73
	s_waitcnt lgkmcnt(1)
	v_mfma_f32_32x32x16_bf16 v[18:33], v[104:107], v[86:89], v[18:33]
	ds_read2_b64 v[82:85], v116 offset0:8 offset1:10
	v_max3_f32 v104, v108, v74, v75
	v_max3_f32 v108, v104, v76, v77
	s_waitcnt lgkmcnt(1)
	v_mfma_f32_32x32x16_bf16 v[2:17], v[100:103], v[86:89], v[2:17]
	ds_read2_b64 v[104:107], v115 offset0:40 offset1:42
	v_max3_f32 v86, v108, v78, v79
	v_max3_f32 v100, v86, v80, v81
	s_waitcnt lgkmcnt(1)
	v_mfma_f32_32x32x16_bf16 v[18:33], v[82:85], v[90:93], v[18:33]
	ds_read2_b64 v[86:89], v116 offset0:12 offset1:14
	v_max3_f32 v100, v100, v34, v35
	v_max3_f32 v100, v100, v36, v37
	s_waitcnt lgkmcnt(1)
	v_mfma_f32_32x32x16_bf16 v[2:17], v[104:107], v[90:93], v[2:17]
	ds_read2_b64 v[82:85], v115 offset0:44 offset1:46
	v_max3_f32 v100, v100, v38, v39
	v_max3_f32 v100, v100, v40, v41
	s_waitcnt lgkmcnt(1)
	v_mfma_f32_32x32x16_bf16 v[18:33], v[86:89], v[94:97], v[18:33]
	v_max3_f32 v86, v100, v42, v43
	v_max3_f32 v86, v86, v44, v45
	s_waitcnt lgkmcnt(0)
	v_mfma_f32_32x32x16_bf16 v[2:17], v[82:85], v[94:97], v[2:17]
	v_max3_f32 v82, v86, v46, v47
	v_max3_f32 v208, v82, v48, v49
	s_setprio 0
	v_add_f32_e32 v82, v98, v99
	v_add_f32_e32 v98, v114, v82
	v_add_f32_e64 v82, v224, v208
	v_add_f32_e64 v83, v225, v209
	v_cmp_gt_f32_e32 vcc, v82, v83
	s_cbranch_vccz .LBB0_932
	v_cmp_lt_i32_e32 vcc, v241, v235
	v_max_f32_e32 v51, v208, v208
	v_max_f32_e32 v52, v223, v223
	v_cndmask_b32_e32 v50, v233, v241, vcc
	v_lshlrev_b32_e32 v50, 2, v50
	ds_bpermute_b32 v50, v50, v208
	s_waitcnt lgkmcnt(0)
	v_max_f32_e32 v50, v50, v50
	v_max_f32_e32 v50, v51, v50
	v_add_f32_e32 v50, v222, v50
	v_max_f32_e32 v82, v52, v50
	v_sub_f32_e32 v50, v223, v82
	v_exp_f32_e32 v52, v50
	v_sub_f32_e32 v50, v222, v82
	v_pk_add_f32 v[80:81], v[80:81], v[50:51] op_sel_hi:[1,0]
	v_pk_add_f32 v[78:79], v[78:79], v[50:51] op_sel_hi:[1,0]
	v_pk_add_f32 v[76:77], v[76:77], v[50:51] op_sel_hi:[1,0]
	v_pk_add_f32 v[74:75], v[74:75], v[50:51] op_sel_hi:[1,0]
	v_pk_add_f32 v[72:73], v[72:73], v[50:51] op_sel_hi:[1,0]
	v_pk_add_f32 v[70:71], v[70:71], v[50:51] op_sel_hi:[1,0]
	v_pk_add_f32 v[68:69], v[68:69], v[50:51] op_sel_hi:[1,0]
	v_pk_add_f32 v[66:67], v[66:67], v[50:51] op_sel_hi:[1,0]
	v_pk_add_f32 v[48:49], v[48:49], v[50:51] op_sel_hi:[1,0]
	v_pk_add_f32 v[46:47], v[46:47], v[50:51] op_sel_hi:[1,0]
	v_pk_add_f32 v[44:45], v[44:45], v[50:51] op_sel_hi:[1,0]
	v_pk_add_f32 v[42:43], v[42:43], v[50:51] op_sel_hi:[1,0]
	v_pk_add_f32 v[40:41], v[40:41], v[50:51] op_sel_hi:[1,0]
	v_pk_add_f32 v[38:39], v[38:39], v[50:51] op_sel_hi:[1,0]
	v_pk_add_f32 v[36:37], v[36:37], v[50:51] op_sel_hi:[1,0]
	v_pk_add_f32 v[34:35], v[34:35], v[50:51] op_sel_hi:[1,0]
	v_xor_b32_e32 v50, 0x80000000, v82
	v_pk_mul_f32 v[16:17], v[16:17], v[52:53] op_sel_hi:[1,0]
	v_pk_mul_f32 v[14:15], v[14:15], v[52:53] op_sel_hi:[1,0]
	v_pk_mul_f32 v[12:13], v[12:13], v[52:53] op_sel_hi:[1,0]
	v_pk_mul_f32 v[10:11], v[10:11], v[52:53] op_sel_hi:[1,0]
	v_pk_mul_f32 v[8:9], v[8:9], v[52:53] op_sel_hi:[1,0]
	v_pk_mul_f32 v[6:7], v[6:7], v[52:53] op_sel_hi:[1,0]
	v_pk_mul_f32 v[4:5], v[4:5], v[52:53] op_sel_hi:[1,0]
	v_pk_mul_f32 v[2:3], v[2:3], v[52:53] op_sel_hi:[1,0]
	v_pk_mul_f32 v[32:33], v[32:33], v[52:53] op_sel_hi:[1,0]
	v_pk_mul_f32 v[30:31], v[30:31], v[52:53] op_sel_hi:[1,0]
	v_pk_mul_f32 v[28:29], v[28:29], v[52:53] op_sel_hi:[1,0]
	v_pk_mul_f32 v[26:27], v[26:27], v[52:53] op_sel_hi:[1,0]
	v_pk_mul_f32 v[24:25], v[24:25], v[52:53] op_sel_hi:[1,0]
	v_pk_mul_f32 v[22:23], v[22:23], v[52:53] op_sel_hi:[1,0]
	v_pk_mul_f32 v[20:21], v[20:21], v[52:53] op_sel_hi:[1,0]
	v_pk_mul_f32 v[18:19], v[18:19], v[52:53] op_sel_hi:[1,0]
	v_mul_f32_e32 v98, v98, v52
	v_mov_b32_e32 v51, v50
	v_mov_b32_e32 v52, v50
	v_mov_b32_e32 v53, v50
	v_mov_b32_e32 v54, v50
	v_mov_b32_e32 v55, v50
	v_mov_b32_e32 v56, v50
	v_mov_b32_e32 v57, v50
	v_mov_b32_e32 v58, v50
	v_mov_b32_e32 v59, v50
	v_mov_b32_e32 v60, v50
	v_mov_b32_e32 v61, v50
	v_mov_b32_e32 v62, v50
	v_mov_b32_e32 v63, v50
	v_mov_b32_e32 v64, v50
	v_mov_b32_e32 v65, v50
	v_mov_b32_e32 v222, v82
	v_mov_b32_e32 v223, v82
	s_branch .LBB0_932

.LBB0_1312:
	s_or_b64 exec, exec, s[0:1]
	v_readlane_b32 s0, v253, 45
	v_mov_b32_e32 v1, v207
	v_readlane_b32 s1, v253, 46
	s_waitcnt lgkmcnt(0)
	s_barrier
	s_andn2_b64 vcc, exec, s[0:1]
	v_readfirstlane_b32 s6, v1
	s_cbranch_vccnz .LBB0_1334
	s_ashr_i32 s7, s6, 6
	v_and_b32_e32 v4, 15, v1
	s_lshl_b32 s8, s7, 4
	v_bitop3_b32 v30, s8, -2, v4 bitop3:0xc8
	v_not_b32_e32 v2, v1
	v_lshlrev_b32_e32 v2, 4, v2
	v_ashrrev_i32_e32 v31, 31, v30
	v_readlane_b32 s0, v253, 47
	v_and_b32_e32 v32, 16, v2
	v_mul_u32_u24_e32 v32, 0x202000, v32
	v_sub_u32_e32 v32, 0x3020c0c, v32
	v_lshlrev_b64 v[2:3], 1, v[30:31]
	v_readlane_b32 s1, v253, 48
	s_and_b32 s10, s8, 48
	v_and_b32_e32 v10, 64, v233
	v_lshl_add_u64 v[36:37], s[0:1], 0, v[2:3]
	v_readlane_b32 s0, v254, 33
	v_and_b32_e32 v33, 63, v1
	v_bfe_u32 v5, v1, 4, 2
	v_or_b32_e32 v6, s8, v4
	v_lshl_add_u64 v[34:35], s[34:35], 0, v[2:3]
	v_ashrrev_i32_e32 v2, 3, v1
	v_and_b32_e32 v52, 48, v1
	v_or_b32_e32 v1, s10, v4
	v_mov_b32_e32 v3, s0
	s_movk_i32 s16, 0x110
	v_or_b32_e32 v9, v10, v4
	s_movk_i32 s15, 0x90
	v_and_b32_e32 v38, -8, v2
	s_ashr_i32 s9, s6, 8
	v_mad_u32_u24 v3, v1, s16, v3
	v_lshlrev_b32_e32 v53, 2, v9
	v_or_b32_e32 v9, v33, v10
	v_mul_lo_u32 v10, v6, s15
	v_lshlrev_b32_e32 v11, 1, v52
	s_lshl_b32 s7, s7, 1
	s_ashr_i32 s11, s6, 7
	v_lshl_add_u32 v7, s9, 7, v3
	v_lshl_or_b32 v56, v9, 2, v242
	v_bitop3_b32 v9, s8, v52, v4 bitop3:0x36
	v_add3_u32 v57, 0, v10, v11
	v_mul_lo_u32 v10, v38, s15
	v_lshlrev_b32_e32 v11, 1, v33
	s_lshl_b32 s8, s9, 6
	s_and_b32 s7, s7, 2
	s_lshl_b32 s12, s11, 4
	s_lshl_b32 s9, s9, 5
	s_movk_i32 s13, 0x88
	v_add3_u32 v58, 0, v10, v11
	v_or_b32_e32 v2, 7, v2
	v_add_u32_e32 v10, 0, v52
	v_add_u32_e32 v62, v3, v52
	v_or_b32_e32 v63, 15, v33
	v_mad_u32_u24 v3, v52, s13, v9
	s_cmp_le_i32 s7, s11
	v_mul_lo_u32 v2, v2, s15
	v_mad_u32_u24 v60, v1, s15, v10
	v_or_b32_e32 v1, s12, v4
	v_lshl_add_u32 v64, v3, 1, 0
	v_mad_u32_u24 v3, v63, s13, v9
	s_cselect_b64 s[66:67], -1, 0
	s_lshl_b32 s13, s7, 4
	v_lshlrev_b32_e32 v8, 3, v5
	v_cmp_eq_u32_e64 s[4:5], 3, v5
	v_add3_u32 v59, 0, v2, v11
	v_lshlrev_b32_e32 v2, 2, v5
	v_mul_lo_u32 v5, v1, s15
	v_lshl_add_u32 v79, v3, 1, 0
	v_or_b32_e32 v3, s13, v4
	s_lshl_b32 s14, s7, 5
	v_mov_b32_e32 v14, 0x60
	v_readlane_b32 s17, v254, 34
	v_add_u32_e32 v5, 0, v5
	v_mad_u32_u24 v3, v3, s16, 0
	v_bitop3_b32 v11, s13, v8, 32 bitop3:0x1e
	v_bitop3_b32 v13, s13, v8, v14 bitop3:0x1e
	s_cmp_lt_i32 s7, s11
	v_lshl_add_u32 v61, v6, 2, s17
	v_lshl_add_u32 v6, v1, 7, v5
	v_add3_u32 v80, v3, v52, s14
	v_lshl_add_u32 v82, v11, 1, v3
	v_lshl_add_u32 v85, v13, 1, v3
	v_bitop3_b32 v3, v8, s12, v14 bitop3:0x36
	s_cselect_b64 s[68:69], -1, 0
	s_or_b32 s11, s13, 16
	v_xor_b32_e32 v9, s12, v8
	v_bitop3_b32 v11, v8, s12, 32 bitop3:0x36
	v_bitop3_b32 v12, v8, s12, 64 bitop3:0x36
	v_lshl_add_u32 v86, v3, 1, v6
	v_or_b32_e32 v3, s11, v4
	v_lshl_add_u32 v81, v9, 1, v6
	v_or_b32_e32 v9, 32, v8
	v_lshl_add_u32 v83, v11, 1, v6
	v_lshl_add_u32 v84, v12, 1, v6
	v_mad_u32_u24 v3, v3, s16, 0
	v_bitop3_b32 v6, s13, v8, 16 bitop3:0x36
	v_or_b32_e32 v11, 64, v8
	v_lshl_add_u32 v87, v6, 1, v3
	v_bitop3_b32 v6, s13, v9, 16 bitop3:0x36
	v_or_b32_e32 v12, 0x60, v8
	v_lshl_add_u32 v88, v6, 1, v3
	v_bitop3_b32 v6, s13, v11, 16 bitop3:0x36
	v_lshl_add_u32 v89, v6, 1, v3
	v_bitop3_b32 v6, s13, v12, 16 bitop3:0x36
	v_or_b32_e32 v91, s9, v4
	v_lshl_add_u32 v90, v6, 1, v3
	v_mul_lo_u32 v6, v91, s16
	v_add_u32_e32 v6, 0, v6
	v_bitop3_b32 v9, v8, s9, 32 bitop3:0x36
	v_lshl_add_u32 v93, v9, 1, v6
	v_bitop3_b32 v9, v8, s9, 64 bitop3:0x36
	s_or_b32 s7, s9, 16
	v_lshl_add_u32 v94, v9, 1, v6
	v_bitop3_b32 v9, v8, s9, v14 bitop3:0x36
	v_or_b32_e32 v96, s7, v4
	v_lshl_add_u32 v95, v9, 1, v6
	v_mul_lo_u32 v9, v96, s16
	v_add_u32_e32 v9, 0, v9
	v_bitop3_b32 v11, s9, v8, 16 bitop3:0x36
	v_lshl_add_u32 v97, v11, 1, v9
	v_bitop3_b32 v11, v8, s7, 32 bitop3:0x36
	v_lshl_add_u32 v98, v11, 1, v9
	v_bitop3_b32 v11, v8, s7, 64 bitop3:0x36
	v_lshl_add_u32 v99, v11, 1, v9
	v_bitop3_b32 v11, v8, s7, v14 bitop3:0x36
	s_and_b32 s6, s6, 0xffffff00
	v_or_b32_e32 v4, s8, v4
	v_or_b32_e32 v13, s13, v2
	v_lshl_add_u32 v100, v11, 1, v9
	s_add_i32 s6, s6, s17
	v_mul_lo_u32 v9, v4, s15
	v_or_b32_e32 v11, 16, v4
	v_or_b32_e32 v12, 32, v4
	v_or_b32_e32 v4, 48, v4
	v_or_b32_e32 v14, 2, v13
	v_lshl_add_u32 v102, v13, 1, v5
	v_or_b32_e32 v5, s11, v2
	v_mul_lo_u32 v3, v91, s15
	v_add3_u32 v92, v6, v52, s8
	v_mul_lo_u32 v6, v96, s15
	v_add_u32_e32 v101, s6, v52
	v_mul_lo_u32 v11, v11, s15
	v_mul_lo_u32 v12, v12, s15
	v_mul_lo_u32 v4, v4, s15
	v_cmp_gt_i32_e64 s[6:7], v13, v1
	v_cmp_lt_i32_e64 s[8:9], v13, v1
	v_cmp_gt_i32_e64 s[12:13], v14, v1
	v_or_b32_e32 v14, 3, v13
	v_cmp_gt_i32_e64 s[16:17], v5, v1
	v_cmp_lt_i32_e64 s[18:19], v5, v1
	v_or_b32_e32 v13, 2, v5
	v_or_b32_e32 v5, 3, v5
	v_ashrrev_i32_e32 v39, 31, v38
	v_or_b32_e32 v54, 64, v53
	v_or_b32_e32 v55, 0x80, v53
	v_cmp_gt_u32_e64 s[0:1], 16, v33
	v_cmp_lt_u32_e64 s[2:3], 31, v33
	v_add_u32_e32 v65, 0x110, v64
	s_waitcnt vmcnt(8)
	v_add_u32_e32 v66, 0x220, v64
	v_add_u32_e32 v67, 0x330, v64
	v_add_u32_e32 v68, 0x440, v64
	v_add_u32_e32 v69, 0x550, v64
	v_add_u32_e32 v70, 0x660, v64
	v_add_u32_e32 v71, 0x770, v64
	v_add_u32_e32 v72, 0x880, v64
	v_add_u32_e32 v73, 0x990, v64
	v_add_u32_e32 v74, 0xaa0, v64
	v_add_u32_e32 v75, 0xbb0, v64
	v_add_u32_e32 v76, 0xcc0, v64
	v_add_u32_e32 v77, 0xdd0, v64
	v_add_u32_e32 v78, 0xee0, v64
	v_cmp_gt_i32_e64 s[14:15], v14, v1
	v_cmp_gt_i32_e64 s[20:21], v13, v1
	v_cmp_gt_i32_e64 s[22:23], v5, v1
	v_mov_b32_e32 v1, v32
	s_lshl_b32 s52, s10, 1
	v_lshlrev_b32_e32 v40, 1, v2
	v_add_u32_e32 v103, v7, v8
	v_add_u32_e32 v104, v10, v3
	v_add_u32_e32 v105, v10, v6
	v_add_u32_e32 v106, v10, v9
	v_add_u32_e32 v107, v10, v11
	v_add_u32_e32 v108, v10, v12
	v_add_u32_e32 v109, v10, v4
	s_mov_b32 s53, s24
	s_branch .LBB0_1315

.LBB0_1317:
	s_waitcnt vmcnt(48)
	v_perm_b32 v26, v115, v115, v32
	v_add_f32_e32 v176, 0, v26
	s_waitcnt vmcnt(45)
	v_perm_b32 v26, v119, v119, v32
	v_add_f32_e32 v177, v176, v26
	s_waitcnt vmcnt(42)
	v_perm_b32 v26, v124, v124, v32
	v_add_f32_e32 v178, v177, v26
	s_waitcnt vmcnt(39)
	v_perm_b32 v26, v132, v132, v32
	v_add_f32_e32 v179, v178, v26
	s_waitcnt vmcnt(36)
	v_perm_b32 v26, v136, v136, v32
	v_add_f32_e32 v180, v179, v26
	s_waitcnt vmcnt(33)
	v_perm_b32 v26, v143, v143, v32
	v_add_f32_e32 v181, v180, v26
	s_waitcnt vmcnt(30)
	v_perm_b32 v26, v146, v146, v32
	v_add_f32_e32 v182, v181, v26
	s_waitcnt vmcnt(27)
	v_perm_b32 v26, v149, v149, v32
	v_add_f32_e32 v183, v182, v26
	s_waitcnt vmcnt(24)
	v_perm_b32 v26, v152, v152, v32
	v_add_f32_e32 v184, v183, v26
	s_waitcnt vmcnt(21)
	v_perm_b32 v26, v155, v155, v32
	v_add_f32_e32 v185, v184, v26
	s_waitcnt vmcnt(18)
	v_perm_b32 v26, v158, v158, v32
	v_add_f32_e32 v186, v185, v26
	s_waitcnt vmcnt(15)
	v_perm_b32 v26, v161, v161, v32
	v_add_f32_e32 v187, v186, v26
	s_waitcnt vmcnt(12)
	v_perm_b32 v26, v164, v164, v32
	v_add_f32_e32 v188, v187, v26
	s_waitcnt vmcnt(9)
	v_perm_b32 v26, v167, v167, v32
	v_add_f32_e32 v189, v188, v26
	s_waitcnt vmcnt(6)
	v_perm_b32 v26, v170, v170, v32
	v_add_f32_e32 v190, v189, v26
	s_waitcnt vmcnt(3)
	v_perm_b32 v26, v173, v173, v32
	v_add_f32_e32 v191, v190, v26
	ds_bpermute_b32 v26, v53, v191
	ds_bpermute_b32 v28, v54, v191
	ds_bpermute_b32 v27, v55, v191
	ds_bpermute_b32 v29, v56, v191
	v_cvt_pk_bf16_f32 v22, v2, v3
	v_cvt_pk_bf16_f32 v23, v4, v5
	v_cvt_pk_bf16_f32 v24, v14, v15
	v_cvt_pk_bf16_f32 v25, v16, v17
	s_waitcnt lgkmcnt(0)
	s_barrier
	ds_write2_b64 v103, v[22:23], v[24:25] offset1:4
	v_cvt_pk_bf16_f32 v22, v6, v7
	v_cvt_pk_bf16_f32 v23, v8, v9
	v_cvt_pk_bf16_f32 v24, v10, v11
	v_cvt_pk_bf16_f32 v25, v12, v13
	ds_write2_b64 v103, v[22:23], v[24:25] offset0:8 offset1:12
	v_cndmask_b32_e64 v22, v26, 0, s[0:1]
	v_cndmask_b32_e64 v23, 0, v28, s[2:3]
	v_add_f32_e32 v22, v22, v23
	v_cndmask_b32_e64 v23, 0, v27, s[4:5]
	v_add_f32_e32 v192, v22, v23
	v_pk_add_f32 v[22:23], v[26:27], v[28:29]
	v_add_f32_e32 v22, v22, v23
	v_add_f32_e32 v23, v176, v192
	v_exp_f32_e32 v25, v23
	v_perm_b32 v24, v116, v116, v32
	v_exp_f32_e64 v26, -v23
	v_exp_f32_e32 v22, v22
	v_mul_f32_e32 v23, v25, v24
	v_cvt_pk_bf16_f32 v23, v23, s0
	ds_write_b16 v64, v23
	v_add_f32_e32 v23, v177, v192
	v_exp_f32_e32 v24, v23
	v_exp_f32_e64 v27, -v23
	v_perm_b32 v25, v121, v121, v32
	v_perm_b32 v29, v122, v122, v1
	v_perm_b32 v28, v118, v118, v32
	v_mul_f32_e32 v23, v24, v25
	v_mul_f32_e32 v24, v26, v28
	v_cvt_pk_bf16_f32 v23, v23, s0
	v_cvt_pk_bf16_f32 v24, v24, s0
	ds_write_b16 v64, v24 offset:17408
	v_pk_mul_f32 v[24:25], v[22:23], v[26:27] op_sel_hi:[0,1]
	ds_write_b16 v65, v23
	v_mul_f32_e32 v23, v27, v29
	v_cvt_pk_bf16_f32 v23, v23, s0
	ds_write_b16 v65, v23 offset:17408
	v_add_f32_e32 v23, v178, v192
	v_pk_mul_f32 v[24:25], v[24:25], v[28:29]
	v_exp_f32_e32 v28, v23
	v_perm_b32 v27, v127, v127, v32
	v_exp_f32_e64 v26, -v23
	v_mul_f32_e32 v23, v28, v27
	v_cvt_pk_bf16_f32 v23, v23, s0
	ds_write_b16 v66, v23
	v_add_f32_e32 v23, v179, v192
	v_exp_f32_e32 v28, v23
	v_perm_b32 v177, v133, v133, v32
	v_exp_f32_e64 v27, -v23
	v_mul_f32_e32 v23, v28, v177
	v_perm_b32 v28, v130, v130, v32
	v_mul_f32_e32 v176, v26, v28
	v_cvt_pk_bf16_f32 v23, v23, s0
	v_perm_b32 v29, v135, v135, v1
	v_cvt_pk_bf16_f32 v176, v176, s0
	ds_write_b16 v66, v176 offset:17408
	v_pk_mul_f32 v[176:177], v[22:23], v[26:27] op_sel_hi:[0,1]
	ds_write_b16 v67, v23
	v_mul_f32_e32 v23, v27, v29
	v_cvt_pk_bf16_f32 v23, v23, s0
	ds_write_b16 v67, v23 offset:17408
	v_add_f32_e32 v23, v180, v192
	v_pk_mul_f32 v[176:177], v[176:177], v[28:29]
	v_exp_f32_e32 v28, v23
	v_perm_b32 v27, v137, v137, v32
	v_exp_f32_e64 v26, -v23
	v_mul_f32_e32 v23, v28, v27
	v_cvt_pk_bf16_f32 v23, v23, s0
	ds_write_b16 v68, v23
	v_add_f32_e32 v23, v181, v192
	v_exp_f32_e32 v28, v23
	v_perm_b32 v179, v144, v144, v32
	v_exp_f32_e64 v27, -v23
	v_mul_f32_e32 v23, v28, v179
	v_perm_b32 v28, v138, v138, v32
	v_mul_f32_e32 v178, v26, v28
	v_cvt_pk_bf16_f32 v23, v23, s0
	v_perm_b32 v29, v145, v145, v1
	v_cvt_pk_bf16_f32 v178, v178, s0
	ds_write_b16 v68, v178 offset:17408
	v_pk_mul_f32 v[178:179], v[22:23], v[26:27] op_sel_hi:[0,1]
	ds_write_b16 v69, v23
	v_mul_f32_e32 v23, v27, v29
	v_cvt_pk_bf16_f32 v23, v23, s0
	ds_write_b16 v69, v23 offset:17408
	v_add_f32_e32 v23, v182, v192
	v_pk_mul_f32 v[178:179], v[178:179], v[28:29]
	v_exp_f32_e32 v28, v23
	v_perm_b32 v27, v147, v147, v32
	v_exp_f32_e64 v26, -v23
	v_mul_f32_e32 v23, v28, v27
	v_cvt_pk_bf16_f32 v23, v23, s0
	ds_write_b16 v70, v23
	v_add_f32_e32 v23, v183, v192
	v_exp_f32_e32 v28, v23
	v_perm_b32 v181, v150, v150, v32
	v_exp_f32_e64 v27, -v23
	v_mul_f32_e32 v23, v28, v181
	v_perm_b32 v28, v148, v148, v32
	v_mul_f32_e32 v180, v26, v28
	v_cvt_pk_bf16_f32 v23, v23, s0
	v_perm_b32 v29, v151, v151, v1
	v_cvt_pk_bf16_f32 v180, v180, s0
	ds_write_b16 v70, v180 offset:17408
	v_pk_mul_f32 v[180:181], v[22:23], v[26:27] op_sel_hi:[0,1]
	ds_write_b16 v71, v23
	v_mul_f32_e32 v23, v27, v29
	v_cvt_pk_bf16_f32 v23, v23, s0
	ds_write_b16 v71, v23 offset:17408
	v_add_f32_e32 v23, v184, v192
	v_pk_mul_f32 v[180:181], v[180:181], v[28:29]
	v_exp_f32_e32 v28, v23
	v_perm_b32 v27, v153, v153, v32
	v_exp_f32_e64 v26, -v23
	v_mul_f32_e32 v23, v28, v27
	v_cvt_pk_bf16_f32 v23, v23, s0
	ds_write_b16 v72, v23
	v_add_f32_e32 v23, v185, v192
	v_exp_f32_e32 v28, v23
	v_perm_b32 v183, v156, v156, v32
	v_exp_f32_e64 v27, -v23
	v_mul_f32_e32 v23, v28, v183
	v_perm_b32 v28, v154, v154, v32
	v_mul_f32_e32 v182, v26, v28
	v_cvt_pk_bf16_f32 v23, v23, s0
	v_perm_b32 v29, v157, v157, v1
	v_cvt_pk_bf16_f32 v182, v182, s0
	ds_write_b16 v72, v182 offset:17408
	v_pk_mul_f32 v[182:183], v[22:23], v[26:27] op_sel_hi:[0,1]
	ds_write_b16 v73, v23
	v_mul_f32_e32 v23, v27, v29
	v_cvt_pk_bf16_f32 v23, v23, s0
	ds_write_b16 v73, v23 offset:17408
	v_add_f32_e32 v23, v186, v192
	v_pk_mul_f32 v[182:183], v[182:183], v[28:29]
	v_exp_f32_e32 v28, v23
	v_perm_b32 v27, v159, v159, v32
	v_exp_f32_e64 v26, -v23
	v_mul_f32_e32 v23, v28, v27
	v_cvt_pk_bf16_f32 v23, v23, s0
	ds_write_b16 v74, v23
	v_add_f32_e32 v23, v187, v192
	v_exp_f32_e32 v28, v23
	v_perm_b32 v185, v162, v162, v32
	v_exp_f32_e64 v27, -v23
	v_mul_f32_e32 v23, v28, v185
	v_perm_b32 v28, v160, v160, v32
	v_mul_f32_e32 v184, v26, v28
	v_cvt_pk_bf16_f32 v23, v23, s0
	v_perm_b32 v29, v163, v163, v1
	v_cvt_pk_bf16_f32 v184, v184, s0
	ds_write_b16 v74, v184 offset:17408
	v_pk_mul_f32 v[184:185], v[22:23], v[26:27] op_sel_hi:[0,1]
	ds_write_b16 v75, v23
	v_mul_f32_e32 v23, v27, v29
	v_cvt_pk_bf16_f32 v23, v23, s0
	ds_write_b16 v75, v23 offset:17408
	v_add_f32_e32 v23, v188, v192
	v_pk_mul_f32 v[184:185], v[184:185], v[28:29]
	v_exp_f32_e32 v28, v23
	v_perm_b32 v27, v165, v165, v32
	v_exp_f32_e64 v26, -v23
	v_mul_f32_e32 v23, v28, v27
	v_cvt_pk_bf16_f32 v23, v23, s0
	ds_write_b16 v76, v23
	v_add_f32_e32 v23, v189, v192
	v_exp_f32_e32 v28, v23
	v_perm_b32 v187, v168, v168, v32
	v_exp_f32_e64 v27, -v23
	v_mul_f32_e32 v23, v28, v187
	v_perm_b32 v28, v166, v166, v32
	v_mul_f32_e32 v186, v26, v28
	v_cvt_pk_bf16_f32 v23, v23, s0
	v_perm_b32 v29, v169, v169, v1
	v_cvt_pk_bf16_f32 v186, v186, s0
	ds_write_b16 v76, v186 offset:17408
	v_pk_mul_f32 v[186:187], v[22:23], v[26:27] op_sel_hi:[0,1]
	ds_write_b16 v77, v23
	v_mul_f32_e32 v23, v27, v29
	v_cvt_pk_bf16_f32 v23, v23, s0
	ds_write_b16 v77, v23 offset:17408
	v_add_f32_e32 v23, v190, v192
	v_exp_f32_e32 v27, v23
	v_perm_b32 v26, v171, v171, v32
	v_pk_mul_f32 v[186:187], v[186:187], v[28:29]
	v_exp_f32_e64 v28, -v23
	v_mul_f32_e32 v23, v27, v26
	v_cvt_pk_bf16_f32 v23, v23, s0
	ds_write_b16 v78, v23
	v_add_f32_e32 v23, v191, v192
	v_exp_f32_e32 v26, v23
	s_waitcnt vmcnt(1)
	v_exp_f32_e64 v29, -v23
	v_perm_b32 v27, v174, v174, v32
	v_perm_b32 v189, v175, v175, v1
	v_perm_b32 v188, v172, v172, v32
	v_mul_f32_e32 v23, v26, v27
	v_mul_f32_e32 v26, v28, v188
	v_cvt_pk_bf16_f32 v23, v23, s0
	v_cvt_pk_bf16_f32 v26, v26, s0
	ds_write_b16 v78, v26 offset:17408
	ds_write_b16 v79, v23
	v_mul_f32_e32 v23, v29, v189
	v_cvt_pk_bf16_f32 v23, v23, s0
	v_pk_mul_f32 v[28:29], v[22:23], v[28:29] op_sel_hi:[0,1]
	v_cvt_pk_bf16_f32 v24, v24, v25
	v_cvt_pk_bf16_f32 v25, v176, v177
	v_cvt_pk_bf16_f32 v26, v178, v179
	v_cvt_pk_bf16_f32 v27, v180, v181
	v_pk_mul_f32 v[28:29], v[28:29], v[188:189]
	ds_write_b16 v79, v23 offset:17408
	v_cvt_pk_bf16_f32 v176, v182, v183
	v_cvt_pk_bf16_f32 v177, v184, v185
	v_cvt_pk_bf16_f32 v178, v186, v187
	v_cvt_pk_bf16_f32 v179, v28, v29
	ds_write_b128 v57, v[24:27] offset:34816
	ds_write_b128 v57, v[176:179] offset:34832
	s_and_saveexec_b64 s[72:73], s[0:1]
	ds_write_b32 v61, v22
	s_or_b64 exec, exec, s[72:73]
	s_cmp_eq_u32 s75, -1
	s_mov_b32 s10, s76
	s_waitcnt vmcnt(0)
	ds_write_b16 v58, v18 offset:53248
	ds_write_b16_d16_hi v58, v18 offset:53392
	ds_write_b16 v58, v19 offset:53536
	ds_write_b16_d16_hi v58, v19 offset:53680
	ds_write_b16 v58, v20 offset:53824
	ds_write_b16_d16_hi v58, v20 offset:53968
	ds_write_b16 v58, v21 offset:54112
	ds_write_b16_d16_hi v59, v21 offset:53248
	s_cbranch_scc1 .LBB0_1325
	s_cmp_gt_u32 s57, 2
	s_mov_b64 s[72:73], -1
	s_cbranch_scc0 .LBB0_1322
	s_and_b64 s[10:11], s[70:71], exec
	s_cselect_b32 s10, s74, s75
	s_add_i32 s10, s10, s65
	s_mov_b64 s[72:73], 0
